# v9 plus GEMM K-loops: A(buf0,half0) LDS-DMA stage issued in phase 3 instead of phase 2 (pieces per phase 2/4/4/6), phase 2 waits vmcnt(6)
# speedup vs baseline: 1.0166x; 1.0166x over previous
; #define PG8_STAGE(bufoff, gbase, voff) do { _Pragma("unroll") for (int _i = 0; _i < 2; ++_i) \
;         __builtin_amdgcn_global_load_lds((const unsigned*)((const char*)(gbase) + (voff)[_i]), (LAS unsigned*)(lds + (bufoff) + ldsw + _i * 8192), 16, 0, 0); } while (0)
; #define PG8_LDA(dst, b, h) do { _Pragma("unroll") for (int m = 0; m < 4; ++m) _Pragma("unroll") for (int k = 0; k < 2; ++k) dst[m][k] = *(const LAS bf16x8*)(lds + PG8_SA(b, h) + aoff + m * 2048 + k * 1024); } while (0)
; #define PG8_LDB(dst, b, h) do { _Pragma("unroll") for (int n = 0; n < 2; ++n) _Pragma("unroll") for (int k = 0; k < 2; ++k) dst[n][k] = *(const LAS bf16x8*)(lds + PG8_SB(b, h) + boff + n * 2048 + k * 1024); } while (0)
; #define PG8_MMA(ai, bj, At, Bt) do { __builtin_amdgcn_s_setprio(1); _Pragma("unroll") for (int m = 0; m < 4; ++m) _Pragma("unroll") for (int n = 0; n < 2; ++n) _Pragma("unroll") for (int k = 0; k < 2; ++k) \
;         acc[ai][bj][m][n] = __builtin_amdgcn_mfma_f32_16x16x32_bf16(Bt[n][k], At[m][k], acc[ai][bj][m][n], 0, 0, 0); __builtin_amdgcn_s_setprio(0); } while (0)
; #define PG8_WAIT_V(n) asm volatile("s_waitcnt vmcnt(" #n ")" ::: "memory")
; #define PG8_WAIT_L(n) asm volatile("s_waitcnt lgkmcnt(" #n ")" ::: "memory")
; #define PG8_BAR __builtin_amdgcn_s_barrier()
; #define PG8_SCHED __builtin_amdgcn_sched_barrier(0)
; template <class Epi, class Sched>
; __device__ __forceinline__ void gemm_phase(LAS unsigned char* lds, const Gemm g, const Sched& S, const Epi& E, const int tid) {
;     ...
;             const char* a1 = cA + (size_t)(t + 1) * kstep;
;             const char* a2 = last ? nA : cA + (size_t)(t + 2) * kstep; const char* b2 = last ? nB : cB + (size_t)(t + 2) * kstep;
;             const char* a3 = a2 + kstep; const char* b3 = b2 + kstep;
;             PG8_LDB(B0, 0, 0); PG8_LDB(B1, 0, 1); PG8_SCHED; PG8_LDA(At, 0, 0); PG8_STAGE(PG8_SA(1, 1), a1 + hstepA, voffA);
;             PG8_WAIT_V(8); PG8_WAIT_L(0); PG8_BAR; PG8_MMA(0, 0, At, B0); PG8_MMA(0, 1, At, B1); PG8_BAR; PG8_SCHED;
;             PG8_LDA(At, 0, 1); PG8_STAGE(PG8_SB(0, 0), b2, voffB); PG8_STAGE(PG8_SB(0, 1), b2 + hstepB, voffB); PG8_STAGE(PG8_SA(0, 0), a2, voffA);
;             PG8_WAIT_V(8); PG8_WAIT_L(0); PG8_BAR; PG8_MMA(1, 0, At, B0); PG8_MMA(1, 1, At, B1); PG8_BAR; PG8_SCHED;
.LBB1_36:
	s_add_u32 s42, s56, 0x100
	s_addc_u32 s43, s57, 0
	s_add_i32 s14, 0, 0x10000
	s_cmpk_eq_i32 s71, 0x54
	s_cselect_b32 s61, s49, s43
	s_cselect_b32 s60, s48, s42
	s_cselect_b32 s59, s53, s45
	s_cselect_b32 s58, s52, s44
	s_add_i32 s72, 0, 0x14000
	v_add_u32_e32 v142, s14, v213
	v_add_u32_e32 v158, s72, v213
	ds_read_b128 v[130:133], v142
	ds_read_b128 v[134:137], v142 offset:1024
	ds_read_b128 v[138:141], v142 offset:2048
	ds_read_b128 v[142:145], v142 offset:3072
	ds_read_b128 v[146:149], v158
	ds_read_b128 v[150:153], v158 offset:1024
	ds_read_b128 v[154:157], v158 offset:2048
	ds_read_b128 v[158:161], v158 offset:3072
	v_lshl_add_u64 v[200:201], s[56:57], 0, v[186:187]
	s_add_i32 m0, s47, 0xc000
	ds_read_b128 v[162:165], v218
	ds_read_b128 v[166:169], v218 offset:1024
	ds_read_b128 v[170:173], v218 offset:2048
	ds_read_b128 v[174:177], v218 offset:3072
	ds_read_b128 v[188:191], v218 offset:4096
	ds_read_b128 v[192:195], v218 offset:5120
	ds_read_b128 v[196:199], v218 offset:6144
	ds_read_b128 v[204:207], v218 offset:7168
	global_load_lds_dwordx4 v[200:201], off
	v_lshl_add_u64 v[200:201], s[56:57], 0, v[184:185]
	s_add_i32 m0, s47, 0xe000
	s_nop 0
	global_load_lds_dwordx4 v[200:201], off
	s_waitcnt vmcnt(8)
	s_waitcnt lgkmcnt(0)
	s_barrier
	s_setprio 1
	s_waitcnt lgkmcnt(0)
	v_mfma_f32_16x16x32_bf16 v[126:129], v[130:133], v[162:165], v[126:129]
	v_mfma_f32_16x16x32_bf16 v[122:125], v[138:141], v[162:165], v[122:125]
	v_mfma_f32_16x16x32_bf16 v[110:113], v[130:133], v[170:173], v[110:113]
	v_mfma_f32_16x16x32_bf16 v[106:109], v[138:141], v[170:173], v[106:109]
	v_mfma_f32_16x16x32_bf16 v[94:97], v[130:133], v[188:191], v[94:97]
	v_mfma_f32_16x16x32_bf16 v[90:93], v[138:141], v[188:191], v[90:93]
	v_mfma_f32_16x16x32_bf16 v[78:81], v[130:133], v[196:199], v[78:81]
	v_mfma_f32_16x16x32_bf16 v[74:77], v[138:141], v[196:199], v[74:77]
	v_mfma_f32_16x16x32_bf16 v[126:129], v[134:137], v[166:169], v[126:129]
	v_mfma_f32_16x16x32_bf16 v[122:125], v[142:145], v[166:169], v[122:125]
	v_mfma_f32_16x16x32_bf16 v[110:113], v[134:137], v[174:177], v[110:113]
	v_mfma_f32_16x16x32_bf16 v[106:109], v[142:145], v[174:177], v[106:109]
	v_mfma_f32_16x16x32_bf16 v[94:97], v[134:137], v[192:195], v[94:97]
	v_mfma_f32_16x16x32_bf16 v[90:93], v[142:145], v[192:195], v[90:93]
	v_mfma_f32_16x16x32_bf16 v[78:81], v[134:137], v[204:207], v[78:81]
	v_mfma_f32_16x16x32_bf16 v[74:77], v[142:145], v[204:207], v[74:77]
	s_setprio 0
	s_setprio 1
	v_mfma_f32_16x16x32_bf16 v[118:121], v[146:149], v[162:165], v[118:121]
	v_mfma_f32_16x16x32_bf16 v[114:117], v[154:157], v[162:165], v[114:117]
	v_mfma_f32_16x16x32_bf16 v[102:105], v[146:149], v[170:173], v[102:105]
	v_mfma_f32_16x16x32_bf16 v[98:101], v[154:157], v[170:173], v[98:101]
	v_mfma_f32_16x16x32_bf16 v[86:89], v[146:149], v[188:191], v[86:89]
	v_mfma_f32_16x16x32_bf16 v[82:85], v[154:157], v[188:191], v[82:85]
	v_mfma_f32_16x16x32_bf16 v[70:73], v[146:149], v[196:199], v[70:73]
	v_mfma_f32_16x16x32_bf16 v[66:69], v[154:157], v[196:199], v[66:69]
	v_mfma_f32_16x16x32_bf16 v[118:121], v[150:153], v[166:169], v[118:121]
	v_mfma_f32_16x16x32_bf16 v[114:117], v[158:161], v[166:169], v[114:117]
	v_mfma_f32_16x16x32_bf16 v[102:105], v[150:153], v[174:177], v[102:105]
	v_mfma_f32_16x16x32_bf16 v[98:101], v[158:161], v[174:177], v[98:101]
	v_mfma_f32_16x16x32_bf16 v[86:89], v[150:153], v[192:195], v[86:89]
	v_mfma_f32_16x16x32_bf16 v[82:85], v[158:161], v[192:195], v[82:85]
	v_mfma_f32_16x16x32_bf16 v[70:73], v[150:153], v[204:207], v[70:73]
	v_mfma_f32_16x16x32_bf16 v[66:69], v[158:161], v[204:207], v[66:69]
	s_setprio 0
	s_barrier
	s_add_i32 s14, s14, s46
	v_lshl_add_u64 v[200:201], s[58:59], 0, v[0:1]
	s_mov_b32 m0, s14
	ds_read_b128 v[162:165], v218 offset:16384
	ds_read_b128 v[166:169], v218 offset:17408
	ds_read_b128 v[170:173], v218 offset:18432
	ds_read_b128 v[174:177], v218 offset:19456
	ds_read_b128 v[188:191], v218 offset:20480
	ds_read_b128 v[192:195], v218 offset:21504
	ds_read_b128 v[196:199], v218 offset:22528
	ds_read_b128 v[204:207], v218 offset:23552
	global_load_lds_dwordx4 v[200:201], off
	s_add_i32 m0, s14, 0x2000
	s_add_u32 s14, s58, 0x160000
	v_lshl_add_u64 v[208:209], s[58:59], 0, v[182:183]
	s_addc_u32 s15, s59, 0
	s_add_i32 s56, s72, s46
	global_load_lds_dwordx4 v[208:209], off
	v_lshl_add_u64 v[210:211], s[14:15], 0, v[0:1]
	s_mov_b32 m0, s56
	v_lshl_add_u64 v[220:221], s[60:61], 0, v[180:181]
	global_load_lds_dwordx4 v[210:211], off
	v_lshl_add_u64 v[210:211], s[14:15], 0, v[182:183]
	s_add_i32 m0, s56, 0x2000
	s_nop 0
	global_load_lds_dwordx4 v[210:211], off
	v_lshl_add_u64 v[210:211], s[60:61], 0, v[178:179]
	s_waitcnt vmcnt(6)
	s_waitcnt lgkmcnt(0)
	s_barrier
; #define PG8_STAGE(bufoff, gbase, voff) do { _Pragma("unroll") for (int _i = 0; _i < 2; ++_i) \
;         __builtin_amdgcn_global_load_lds((const unsigned*)((const char*)(gbase) + (voff)[_i]), (LAS unsigned*)(lds + (bufoff) + ldsw + _i * 8192), 16, 0, 0); } while (0)
; #define PG8_LDA(dst, b, h) do { _Pragma("unroll") for (int m = 0; m < 4; ++m) _Pragma("unroll") for (int k = 0; k < 2; ++k) dst[m][k] = *(const LAS bf16x8*)(lds + PG8_SA(b, h) + aoff + m * 2048 + k * 1024); } while (0)
; #define PG8_LDB(dst, b, h) do { _Pragma("unroll") for (int n = 0; n < 2; ++n) _Pragma("unroll") for (int k = 0; k < 2; ++k) dst[n][k] = *(const LAS bf16x8*)(lds + PG8_SB(b, h) + boff + n * 2048 + k * 1024); } while (0)
; #define PG8_MMA(ai, bj, At, Bt) do { __builtin_amdgcn_s_setprio(1); _Pragma("unroll") for (int m = 0; m < 4; ++m) _Pragma("unroll") for (int n = 0; n < 2; ++n) _Pragma("unroll") for (int k = 0; k < 2; ++k) \
;         acc[ai][bj][m][n] = __builtin_amdgcn_mfma_f32_16x16x32_bf16(Bt[n][k], At[m][k], acc[ai][bj][m][n], 0, 0, 0); __builtin_amdgcn_s_setprio(0); } while (0)
; #define PG8_WAIT_V(n) asm volatile("s_waitcnt vmcnt(" #n ")" ::: "memory")
; #define PG8_WAIT_L(n) asm volatile("s_waitcnt lgkmcnt(" #n ")" ::: "memory")
; #define PG8_BAR __builtin_amdgcn_s_barrier()
; #define PG8_SCHED __builtin_amdgcn_sched_barrier(0)
; template <class Epi, class Sched>
; __device__ __forceinline__ void gemm_phase(LAS unsigned char* lds, const Gemm g, const Sched& S, const Epi& E, const int tid) {
;     ...
;             PG8_WAIT_V(8); PG8_WAIT_L(0); PG8_BAR; PG8_MMA(1, 0, At, B0); PG8_MMA(1, 1, At, B1); PG8_BAR; PG8_SCHED;
;             PG8_LDB(B0, 1, 0); PG8_LDB(B1, 1, 1); PG8_SCHED; PG8_LDA(At, 1, 0); PG8_STAGE(PG8_SA(0, 1), a2 + hstepA, voffA);
;             PG8_WAIT_V(8); PG8_WAIT_L(0); PG8_BAR; PG8_MMA(0, 0, At, B0); PG8_MMA(0, 1, At, B1); PG8_BAR; PG8_SCHED;
	s_setprio 1
	s_waitcnt lgkmcnt(0)
	v_mfma_f32_16x16x32_bf16 v[62:65], v[130:133], v[162:165], v[62:65]
	v_mfma_f32_16x16x32_bf16 v[58:61], v[138:141], v[162:165], v[58:61]
	v_mfma_f32_16x16x32_bf16 v[46:49], v[130:133], v[170:173], v[46:49]
	v_mfma_f32_16x16x32_bf16 v[42:45], v[138:141], v[170:173], v[42:45]
	v_mfma_f32_16x16x32_bf16 v[30:33], v[130:133], v[188:191], v[30:33]
	v_mfma_f32_16x16x32_bf16 v[26:29], v[138:141], v[188:191], v[26:29]
	v_mfma_f32_16x16x32_bf16 v[14:17], v[130:133], v[196:199], v[14:17]
	v_mfma_f32_16x16x32_bf16 v[10:13], v[138:141], v[196:199], v[10:13]
	v_mfma_f32_16x16x32_bf16 v[62:65], v[134:137], v[166:169], v[62:65]
	v_mfma_f32_16x16x32_bf16 v[58:61], v[142:145], v[166:169], v[58:61]
	v_mfma_f32_16x16x32_bf16 v[46:49], v[134:137], v[174:177], v[46:49]
	v_mfma_f32_16x16x32_bf16 v[42:45], v[142:145], v[174:177], v[42:45]
	v_mfma_f32_16x16x32_bf16 v[30:33], v[134:137], v[192:195], v[30:33]
	v_mfma_f32_16x16x32_bf16 v[26:29], v[142:145], v[192:195], v[26:29]
	v_mfma_f32_16x16x32_bf16 v[14:17], v[134:137], v[204:207], v[14:17]
	v_mfma_f32_16x16x32_bf16 v[10:13], v[142:145], v[204:207], v[10:13]
	s_setprio 0
	s_setprio 1
	v_mfma_f32_16x16x32_bf16 v[54:57], v[146:149], v[162:165], v[54:57]
	v_mfma_f32_16x16x32_bf16 v[50:53], v[154:157], v[162:165], v[50:53]
	v_mfma_f32_16x16x32_bf16 v[38:41], v[146:149], v[170:173], v[38:41]
	v_mfma_f32_16x16x32_bf16 v[34:37], v[154:157], v[170:173], v[34:37]
	v_mfma_f32_16x16x32_bf16 v[22:25], v[146:149], v[188:191], v[22:25]
	v_mfma_f32_16x16x32_bf16 v[18:21], v[154:157], v[188:191], v[18:21]
	v_mfma_f32_16x16x32_bf16 v[6:9], v[146:149], v[196:199], v[6:9]
	v_mfma_f32_16x16x32_bf16 v[2:5], v[154:157], v[196:199], v[2:5]
	v_mfma_f32_16x16x32_bf16 v[54:57], v[150:153], v[166:169], v[54:57]
	v_mfma_f32_16x16x32_bf16 v[50:53], v[158:161], v[166:169], v[50:53]
	v_mfma_f32_16x16x32_bf16 v[38:41], v[150:153], v[174:177], v[38:41]
	v_mfma_f32_16x16x32_bf16 v[34:37], v[158:161], v[174:177], v[34:37]
	v_mfma_f32_16x16x32_bf16 v[22:25], v[150:153], v[192:195], v[22:25]
	v_mfma_f32_16x16x32_bf16 v[18:21], v[158:161], v[192:195], v[18:21]
	v_mfma_f32_16x16x32_bf16 v[6:9], v[150:153], v[204:207], v[6:9]
	v_mfma_f32_16x16x32_bf16 v[2:5], v[158:161], v[204:207], v[2:5]
	s_setprio 0
	s_barrier
	s_add_i32 s56, 0, 0x18000
	s_add_i32 s57, 0, 0x1c000
	v_add_u32_e32 v142, s56, v213
	v_add_u32_e32 v158, s57, v213
	ds_read_b128 v[130:133], v142
	ds_read_b128 v[134:137], v142 offset:1024
	ds_read_b128 v[138:141], v142 offset:2048
	ds_read_b128 v[142:145], v142 offset:3072
	ds_read_b128 v[146:149], v158
	ds_read_b128 v[150:153], v158 offset:1024
	ds_read_b128 v[154:157], v158 offset:2048
	ds_read_b128 v[158:161], v158 offset:3072
	s_add_u32 s14, s60, 0x160000
	s_addc_u32 s15, s61, 0
	s_mov_b32 m0, s47
	s_nop 0
	global_load_lds_dwordx4 v[210:211], off
	s_mov_b32 m0, s62
	s_nop 0
	global_load_lds_dwordx4 v[220:221], off
	s_mov_b32 m0, s63
	v_lshl_add_u64 v[222:223], s[14:15], 0, v[178:179]
	ds_read_b128 v[162:165], v218 offset:32768
	ds_read_b128 v[166:169], v218 offset:33792
	ds_read_b128 v[170:173], v218 offset:34816
	ds_read_b128 v[174:177], v218 offset:35840
	ds_read_b128 v[188:191], v218 offset:36864
	ds_read_b128 v[192:195], v218 offset:37888
	ds_read_b128 v[196:199], v218 offset:38912
	ds_read_b128 v[204:207], v218 offset:39936
	global_load_lds_dwordx4 v[222:223], off
	v_lshl_add_u64 v[222:223], s[14:15], 0, v[180:181]
	s_mov_b32 m0, s64
	s_nop 0
	global_load_lds_dwordx4 v[222:223], off
	s_waitcnt vmcnt(8)
	s_waitcnt lgkmcnt(0)
	s_barrier
	s_setprio 1
	s_waitcnt lgkmcnt(0)
	v_mfma_f32_16x16x32_bf16 v[126:129], v[130:133], v[162:165], v[126:129]
	v_mfma_f32_16x16x32_bf16 v[122:125], v[138:141], v[162:165], v[122:125]
	v_mfma_f32_16x16x32_bf16 v[110:113], v[130:133], v[170:173], v[110:113]
	v_mfma_f32_16x16x32_bf16 v[106:109], v[138:141], v[170:173], v[106:109]
	v_mfma_f32_16x16x32_bf16 v[94:97], v[130:133], v[188:191], v[94:97]
	v_mfma_f32_16x16x32_bf16 v[90:93], v[138:141], v[188:191], v[90:93]
	v_mfma_f32_16x16x32_bf16 v[78:81], v[130:133], v[196:199], v[78:81]
	v_mfma_f32_16x16x32_bf16 v[74:77], v[138:141], v[196:199], v[74:77]
	v_mfma_f32_16x16x32_bf16 v[126:129], v[134:137], v[166:169], v[126:129]
	v_mfma_f32_16x16x32_bf16 v[122:125], v[142:145], v[166:169], v[122:125]
	v_mfma_f32_16x16x32_bf16 v[110:113], v[134:137], v[174:177], v[110:113]
	v_mfma_f32_16x16x32_bf16 v[106:109], v[142:145], v[174:177], v[106:109]
	v_mfma_f32_16x16x32_bf16 v[94:97], v[134:137], v[192:195], v[94:97]
	v_mfma_f32_16x16x32_bf16 v[90:93], v[142:145], v[192:195], v[90:93]
	v_mfma_f32_16x16x32_bf16 v[78:81], v[134:137], v[204:207], v[78:81]
	v_mfma_f32_16x16x32_bf16 v[74:77], v[142:145], v[204:207], v[74:77]
	s_setprio 0
	s_setprio 1
	v_mfma_f32_16x16x32_bf16 v[118:121], v[146:149], v[162:165], v[118:121]
	v_mfma_f32_16x16x32_bf16 v[114:117], v[154:157], v[162:165], v[114:117]
	v_mfma_f32_16x16x32_bf16 v[102:105], v[146:149], v[170:173], v[102:105]
	v_mfma_f32_16x16x32_bf16 v[98:101], v[154:157], v[170:173], v[98:101]
	v_mfma_f32_16x16x32_bf16 v[86:89], v[146:149], v[188:191], v[86:89]
	v_mfma_f32_16x16x32_bf16 v[82:85], v[154:157], v[188:191], v[82:85]
	v_mfma_f32_16x16x32_bf16 v[70:73], v[146:149], v[196:199], v[70:73]
	v_mfma_f32_16x16x32_bf16 v[66:69], v[154:157], v[196:199], v[66:69]
	v_mfma_f32_16x16x32_bf16 v[118:121], v[150:153], v[166:169], v[118:121]
	v_mfma_f32_16x16x32_bf16 v[114:117], v[158:161], v[166:169], v[114:117]
	v_mfma_f32_16x16x32_bf16 v[102:105], v[150:153], v[174:177], v[102:105]
	v_mfma_f32_16x16x32_bf16 v[98:101], v[158:161], v[174:177], v[98:101]
	v_mfma_f32_16x16x32_bf16 v[86:89], v[150:153], v[192:195], v[86:89]
	v_mfma_f32_16x16x32_bf16 v[82:85], v[158:161], v[192:195], v[82:85]
	v_mfma_f32_16x16x32_bf16 v[70:73], v[150:153], v[204:207], v[70:73]
	v_mfma_f32_16x16x32_bf16 v[66:69], v[158:161], v[204:207], v[66:69]
	s_setprio 0
	s_barrier
; #define PG8_STAGE(bufoff, gbase, voff) do { _Pragma("unroll") for (int _i = 0; _i < 2; ++_i) \
;         __builtin_amdgcn_global_load_lds((const unsigned*)((const char*)(gbase) + (voff)[_i]), (LAS unsigned*)(lds + (bufoff) + ldsw + _i * 8192), 16, 0, 0); } while (0)
; #define PG8_LDA(dst, b, h) do { _Pragma("unroll") for (int m = 0; m < 4; ++m) _Pragma("unroll") for (int k = 0; k < 2; ++k) dst[m][k] = *(const LAS bf16x8*)(lds + PG8_SA(b, h) + aoff + m * 2048 + k * 1024); } while (0)
; #define PG8_MMA(ai, bj, At, Bt) do { __builtin_amdgcn_s_setprio(1); _Pragma("unroll") for (int m = 0; m < 4; ++m) _Pragma("unroll") for (int n = 0; n < 2; ++n) _Pragma("unroll") for (int k = 0; k < 2; ++k) \
;         acc[ai][bj][m][n] = __builtin_amdgcn_mfma_f32_16x16x32_bf16(Bt[n][k], At[m][k], acc[ai][bj][m][n], 0, 0, 0); __builtin_amdgcn_s_setprio(0); } while (0)
; #define PG8_WAIT_V(n) asm volatile("s_waitcnt vmcnt(" #n ")" ::: "memory")
; #define PG8_WAIT_L(n) asm volatile("s_waitcnt lgkmcnt(" #n ")" ::: "memory")
; #define PG8_BAR __builtin_amdgcn_s_barrier()
; #define PG8_SCHED __builtin_amdgcn_sched_barrier(0)
; template <class Epi, class Sched>
; __device__ __forceinline__ void gemm_phase(LAS unsigned char* lds, const Gemm g, const Sched& S, const Epi& E, const int tid) {
;     ...
;             PG8_LDA(At, 1, 1); PG8_STAGE(PG8_SB(1, 0), b3, voffB); PG8_STAGE(PG8_SB(1, 1), b3 + hstepB, voffB); PG8_STAGE(PG8_SA(1, 0), a3, voffA);
;             PG8_WAIT_V(8); PG8_WAIT_L(0); PG8_BAR; PG8_MMA(1, 0, At, B0); PG8_MMA(1, 1, At, B1); PG8_BAR; PG8_SCHED;
;         }
	s_add_i32 s14, s56, s46
	v_lshl_add_u64 v[200:201], v[200:201], 0, s[90:91]
	s_mov_b32 m0, s14
	ds_read_b128 v[162:165], v218 offset:49152
	ds_read_b128 v[166:169], v218 offset:50176
	ds_read_b128 v[170:173], v218 offset:51200
	ds_read_b128 v[174:177], v218 offset:52224
	ds_read_b128 v[188:191], v218 offset:53248
	ds_read_b128 v[192:195], v218 offset:54272
	ds_read_b128 v[196:199], v218 offset:55296
	ds_read_b128 v[204:207], v218 offset:56320
	global_load_lds_dwordx4 v[200:201], off
	s_add_i32 m0, s14, 0x2000
	s_add_u32 s14, s58, 0x160080
	v_lshl_add_u64 v[200:201], v[208:209], 0, s[90:91]
	s_addc_u32 s15, s59, 0
	s_add_i32 s56, s57, s46
	global_load_lds_dwordx4 v[200:201], off
	v_lshl_add_u64 v[200:201], s[14:15], 0, v[0:1]
	s_mov_b32 m0, s56
	s_nop 0
	global_load_lds_dwordx4 v[200:201], off
	v_lshl_add_u64 v[200:201], s[14:15], 0, v[182:183]
	s_add_i32 m0, s56, 0x2000
	s_nop 0
	global_load_lds_dwordx4 v[200:201], off
	v_lshl_add_u64 v[200:201], v[210:211], 0, s[90:91]
	s_mov_b32 m0, s65
	s_nop 0
	global_load_lds_dwordx4 v[200:201], off
	v_lshl_add_u64 v[200:201], v[220:221], 0, s[90:91]
	s_mov_b32 m0, s66
	s_nop 0
	global_load_lds_dwordx4 v[200:201], off
	s_waitcnt vmcnt(8)
	s_waitcnt lgkmcnt(0)
	s_barrier
	s_setprio 1
	s_waitcnt lgkmcnt(0)
	v_mfma_f32_16x16x32_bf16 v[62:65], v[130:133], v[162:165], v[62:65]
	v_mfma_f32_16x16x32_bf16 v[58:61], v[138:141], v[162:165], v[58:61]
	v_mfma_f32_16x16x32_bf16 v[46:49], v[130:133], v[170:173], v[46:49]
	v_mfma_f32_16x16x32_bf16 v[42:45], v[138:141], v[170:173], v[42:45]
	v_mfma_f32_16x16x32_bf16 v[30:33], v[130:133], v[188:191], v[30:33]
	v_mfma_f32_16x16x32_bf16 v[26:29], v[138:141], v[188:191], v[26:29]
	v_mfma_f32_16x16x32_bf16 v[14:17], v[130:133], v[196:199], v[14:17]
	v_mfma_f32_16x16x32_bf16 v[10:13], v[138:141], v[196:199], v[10:13]
	v_mfma_f32_16x16x32_bf16 v[62:65], v[134:137], v[166:169], v[62:65]
	v_mfma_f32_16x16x32_bf16 v[58:61], v[142:145], v[166:169], v[58:61]
	v_mfma_f32_16x16x32_bf16 v[46:49], v[134:137], v[174:177], v[46:49]
	v_mfma_f32_16x16x32_bf16 v[42:45], v[142:145], v[174:177], v[42:45]
	v_mfma_f32_16x16x32_bf16 v[30:33], v[134:137], v[192:195], v[30:33]
	v_mfma_f32_16x16x32_bf16 v[26:29], v[142:145], v[192:195], v[26:29]
	v_mfma_f32_16x16x32_bf16 v[14:17], v[134:137], v[204:207], v[14:17]
	v_mfma_f32_16x16x32_bf16 v[10:13], v[142:145], v[204:207], v[10:13]
	s_setprio 0
	s_setprio 1
	v_mfma_f32_16x16x32_bf16 v[54:57], v[146:149], v[162:165], v[54:57]
	v_mfma_f32_16x16x32_bf16 v[50:53], v[154:157], v[162:165], v[50:53]
	v_mfma_f32_16x16x32_bf16 v[38:41], v[146:149], v[170:173], v[38:41]
	v_mfma_f32_16x16x32_bf16 v[34:37], v[154:157], v[170:173], v[34:37]
	v_mfma_f32_16x16x32_bf16 v[22:25], v[146:149], v[188:191], v[22:25]
	v_mfma_f32_16x16x32_bf16 v[18:21], v[154:157], v[188:191], v[18:21]
	v_mfma_f32_16x16x32_bf16 v[6:9], v[146:149], v[196:199], v[6:9]
	v_mfma_f32_16x16x32_bf16 v[2:5], v[154:157], v[196:199], v[2:5]
	v_mfma_f32_16x16x32_bf16 v[54:57], v[150:153], v[166:169], v[54:57]
	v_mfma_f32_16x16x32_bf16 v[50:53], v[158:161], v[166:169], v[50:53]
	v_mfma_f32_16x16x32_bf16 v[38:41], v[150:153], v[174:177], v[38:41]
	v_mfma_f32_16x16x32_bf16 v[34:37], v[158:161], v[174:177], v[34:37]
	v_mfma_f32_16x16x32_bf16 v[22:25], v[150:153], v[192:195], v[22:25]
	v_mfma_f32_16x16x32_bf16 v[18:21], v[158:161], v[192:195], v[18:21]
	v_mfma_f32_16x16x32_bf16 v[6:9], v[150:153], v[204:207], v[6:9]
	v_mfma_f32_16x16x32_bf16 v[2:5], v[158:161], v[204:207], v[2:5]
	s_setprio 0
	s_barrier
	s_add_i32 s71, s71, 2
	s_add_u32 s44, s44, 0x100
	s_addc_u32 s45, s45, 0
	s_cmpk_gt_u32 s71, 0x55
	s_mov_b64 s[56:57], s[42:43]
	s_cbranch_scc0 .LBB1_36
	s_and_b64 vcc, exec, s[36:37]
	s_cbranch_vccz .LBB1_39
	s_barrier

; #define PG8_STAGE(bufoff, gbase, voff) do { _Pragma("unroll") for (int _i = 0; _i < 2; ++_i) \
;         __builtin_amdgcn_global_load_lds((const unsigned*)((const char*)(gbase) + (voff)[_i]), (LAS unsigned*)(lds + (bufoff) + ldsw + _i * 8192), 16, 0, 0); } while (0)
; #define PG8_LDA(dst, b, h) do { _Pragma("unroll") for (int m = 0; m < 4; ++m) _Pragma("unroll") for (int k = 0; k < 2; ++k) dst[m][k] = *(const LAS bf16x8*)(lds + PG8_SA(b, h) + aoff + m * 2048 + k * 1024); } while (0)
; #define PG8_LDB(dst, b, h) do { _Pragma("unroll") for (int n = 0; n < 2; ++n) _Pragma("unroll") for (int k = 0; k < 2; ++k) dst[n][k] = *(const LAS bf16x8*)(lds + PG8_SB(b, h) + boff + n * 2048 + k * 1024); } while (0)
; #define PG8_MMA(ai, bj, At, Bt) do { __builtin_amdgcn_s_setprio(1); _Pragma("unroll") for (int m = 0; m < 4; ++m) _Pragma("unroll") for (int n = 0; n < 2; ++n) _Pragma("unroll") for (int k = 0; k < 2; ++k) \
;         acc[ai][bj][m][n] = __builtin_amdgcn_mfma_f32_16x16x32_bf16(Bt[n][k], At[m][k], acc[ai][bj][m][n], 0, 0, 0); __builtin_amdgcn_s_setprio(0); } while (0)
; #define PG8_WAIT_V(n) asm volatile("s_waitcnt vmcnt(" #n ")" ::: "memory")
; #define PG8_WAIT_L(n) asm volatile("s_waitcnt lgkmcnt(" #n ")" ::: "memory")
; #define PG8_BAR __builtin_amdgcn_s_barrier()
; #define PG8_SCHED __builtin_amdgcn_sched_barrier(0)
; template <class Epi, class Sched>
; __device__ __forceinline__ void gemm_phase(LAS unsigned char* lds, const Gemm g, const Sched& S, const Epi& E, const int tid) {
;     ...
;             const char* a1 = cA + (size_t)(t + 1) * kstep;
;             const char* a2 = last ? nA : cA + (size_t)(t + 2) * kstep; const char* b2 = last ? nB : cB + (size_t)(t + 2) * kstep;
;             const char* a3 = a2 + kstep; const char* b3 = b2 + kstep;
;             PG8_LDB(B0, 0, 0); PG8_LDB(B1, 0, 1); PG8_SCHED; PG8_LDA(At, 0, 0); PG8_STAGE(PG8_SA(1, 1), a1 + hstepA, voffA);
;             PG8_WAIT_V(8); PG8_WAIT_L(0); PG8_BAR; PG8_MMA(0, 0, At, B0); PG8_MMA(0, 1, At, B1); PG8_BAR; PG8_SCHED;
;             PG8_LDA(At, 0, 1); PG8_STAGE(PG8_SB(0, 0), b2, voffB); PG8_STAGE(PG8_SB(0, 1), b2 + hstepB, voffB); PG8_STAGE(PG8_SA(0, 0), a2, voffA);
;             PG8_WAIT_V(8); PG8_WAIT_L(0); PG8_BAR; PG8_MMA(1, 0, At, B0); PG8_MMA(1, 1, At, B1); PG8_BAR; PG8_SCHED;
.LBB1_87:
	s_add_u32 s14, s58, 0xfff80080
	s_addc_u32 s15, s59, -1
	s_add_i32 s70, 0, 0x10000
	s_cmp_eq_u32 s45, 28
	s_cselect_b32 s63, s37, s15
	s_cselect_b32 s62, s53, s14
	v_add_u32_e32 v144, s70, v147
	s_cselect_b32 s61, s41, s44
	s_cselect_b32 s60, s68, s69
	s_add_i32 s71, 0, 0x14000
	ds_read_b128 v[140:143], v144
	ds_read_b128 v[158:161], v144 offset:1024
	ds_read_b128 v[162:165], v144 offset:2048
	ds_read_b128 v[166:169], v144 offset:3072
	v_add_u32_e32 v144, s71, v147
	ds_read_b128 v[170:173], v144
	ds_read_b128 v[174:177], v144 offset:1024
	ds_read_b128 v[178:181], v144 offset:2048
	ds_read_b128 v[182:185], v144 offset:3072
	v_lshl_add_u64 v[220:221], s[58:59], 0, v[138:139]
	s_add_i32 m0, s47, 0xc000
	ds_read_b128 v[186:189], v157
	ds_read_b128 v[190:193], v157 offset:1024
	ds_read_b128 v[194:197], v157 offset:2048
	ds_read_b128 v[198:201], v157 offset:3072
	ds_read_b128 v[204:207], v157 offset:4096
	ds_read_b128 v[208:211], v157 offset:5120
	ds_read_b128 v[212:215], v157 offset:6144
	ds_read_b128 v[216:219], v157 offset:7168
	global_load_lds_dwordx4 v[220:221], off
	v_lshl_add_u64 v[220:221], s[58:59], 0, v[136:137]
	s_add_i32 m0, s47, 0xe000
	s_nop 0
	global_load_lds_dwordx4 v[220:221], off
	s_waitcnt vmcnt(8)
	s_waitcnt lgkmcnt(0)
	s_barrier
	s_setprio 1
	s_waitcnt lgkmcnt(0)
	v_mfma_f32_16x16x32_bf16 v[126:129], v[140:143], v[186:189], v[126:129]
	v_mfma_f32_16x16x32_bf16 v[118:121], v[162:165], v[186:189], v[118:121]
	v_mfma_f32_16x16x32_bf16 v[110:113], v[140:143], v[194:197], v[110:113]
	v_mfma_f32_16x16x32_bf16 v[106:109], v[162:165], v[194:197], v[106:109]
	v_mfma_f32_16x16x32_bf16 v[94:97], v[140:143], v[204:207], v[94:97]
	v_mfma_f32_16x16x32_bf16 v[90:93], v[162:165], v[204:207], v[90:93]
	v_mfma_f32_16x16x32_bf16 v[78:81], v[140:143], v[212:215], v[78:81]
	v_mfma_f32_16x16x32_bf16 v[74:77], v[162:165], v[212:215], v[74:77]
	v_mfma_f32_16x16x32_bf16 v[126:129], v[158:161], v[190:193], v[126:129]
	v_mfma_f32_16x16x32_bf16 v[118:121], v[166:169], v[190:193], v[118:121]
	v_mfma_f32_16x16x32_bf16 v[110:113], v[158:161], v[198:201], v[110:113]
	v_mfma_f32_16x16x32_bf16 v[106:109], v[166:169], v[198:201], v[106:109]
	v_mfma_f32_16x16x32_bf16 v[94:97], v[158:161], v[208:211], v[94:97]
	v_mfma_f32_16x16x32_bf16 v[90:93], v[166:169], v[208:211], v[90:93]
	v_mfma_f32_16x16x32_bf16 v[78:81], v[158:161], v[216:219], v[78:81]
	v_mfma_f32_16x16x32_bf16 v[74:77], v[166:169], v[216:219], v[74:77]
	s_setprio 0
	s_setprio 1
	v_mfma_f32_16x16x32_bf16 v[122:125], v[170:173], v[186:189], v[122:125]
	v_mfma_f32_16x16x32_bf16 v[114:117], v[178:181], v[186:189], v[114:117]
	v_mfma_f32_16x16x32_bf16 v[102:105], v[170:173], v[194:197], v[102:105]
	v_mfma_f32_16x16x32_bf16 v[98:101], v[178:181], v[194:197], v[98:101]
	v_mfma_f32_16x16x32_bf16 v[86:89], v[170:173], v[204:207], v[86:89]
	v_mfma_f32_16x16x32_bf16 v[82:85], v[178:181], v[204:207], v[82:85]
	v_mfma_f32_16x16x32_bf16 v[70:73], v[170:173], v[212:215], v[70:73]
	v_mfma_f32_16x16x32_bf16 v[66:69], v[178:181], v[212:215], v[66:69]
	v_mfma_f32_16x16x32_bf16 v[122:125], v[174:177], v[190:193], v[122:125]
	v_mfma_f32_16x16x32_bf16 v[114:117], v[182:185], v[190:193], v[114:117]
	v_mfma_f32_16x16x32_bf16 v[102:105], v[174:177], v[198:201], v[102:105]
	v_mfma_f32_16x16x32_bf16 v[98:101], v[182:185], v[198:201], v[98:101]
	v_mfma_f32_16x16x32_bf16 v[86:89], v[174:177], v[208:211], v[86:89]
	v_mfma_f32_16x16x32_bf16 v[82:85], v[182:185], v[208:211], v[82:85]
	v_mfma_f32_16x16x32_bf16 v[70:73], v[174:177], v[216:219], v[70:73]
	v_mfma_f32_16x16x32_bf16 v[66:69], v[182:185], v[216:219], v[66:69]
	s_setprio 0
	s_barrier
	s_add_i32 s14, s70, s46
	v_lshl_add_u64 v[220:221], s[60:61], 0, v[0:1]
	s_mov_b32 m0, s14
	ds_read_b128 v[186:189], v157 offset:16384
	ds_read_b128 v[190:193], v157 offset:17408
	ds_read_b128 v[194:197], v157 offset:18432
	ds_read_b128 v[198:201], v157 offset:19456
	ds_read_b128 v[204:207], v157 offset:20480
	ds_read_b128 v[208:211], v157 offset:21504
	ds_read_b128 v[212:215], v157 offset:22528
	ds_read_b128 v[216:219], v157 offset:23552
	global_load_lds_dwordx4 v[220:221], off
	s_add_i32 m0, s14, 0x2000
	s_add_u32 s14, s60, 0x80000
	v_lshl_add_u64 v[222:223], s[60:61], 0, v[130:131]
	s_addc_u32 s15, s61, 0
	s_add_i32 s70, s71, s46
	global_load_lds_dwordx4 v[222:223], off
	v_lshl_add_u64 v[224:225], s[14:15], 0, v[0:1]
	s_mov_b32 m0, s70
	v_lshl_add_u64 v[226:227], s[62:63], 0, v[132:133]
	global_load_lds_dwordx4 v[224:225], off
	v_lshl_add_u64 v[224:225], s[14:15], 0, v[130:131]
	s_add_i32 m0, s70, 0x2000
	s_nop 0
	global_load_lds_dwordx4 v[224:225], off
	v_lshl_add_u64 v[224:225], s[62:63], 0, v[134:135]
	s_waitcnt vmcnt(6)
	s_waitcnt lgkmcnt(0)
	s_barrier
; #define PG8_STAGE(bufoff, gbase, voff) do { _Pragma("unroll") for (int _i = 0; _i < 2; ++_i) \
;         __builtin_amdgcn_global_load_lds((const unsigned*)((const char*)(gbase) + (voff)[_i]), (LAS unsigned*)(lds + (bufoff) + ldsw + _i * 8192), 16, 0, 0); } while (0)
; #define PG8_LDA(dst, b, h) do { _Pragma("unroll") for (int m = 0; m < 4; ++m) _Pragma("unroll") for (int k = 0; k < 2; ++k) dst[m][k] = *(const LAS bf16x8*)(lds + PG8_SA(b, h) + aoff + m * 2048 + k * 1024); } while (0)
; #define PG8_LDB(dst, b, h) do { _Pragma("unroll") for (int n = 0; n < 2; ++n) _Pragma("unroll") for (int k = 0; k < 2; ++k) dst[n][k] = *(const LAS bf16x8*)(lds + PG8_SB(b, h) + boff + n * 2048 + k * 1024); } while (0)
; #define PG8_MMA(ai, bj, At, Bt) do { __builtin_amdgcn_s_setprio(1); _Pragma("unroll") for (int m = 0; m < 4; ++m) _Pragma("unroll") for (int n = 0; n < 2; ++n) _Pragma("unroll") for (int k = 0; k < 2; ++k) \
;         acc[ai][bj][m][n] = __builtin_amdgcn_mfma_f32_16x16x32_bf16(Bt[n][k], At[m][k], acc[ai][bj][m][n], 0, 0, 0); __builtin_amdgcn_s_setprio(0); } while (0)
; #define PG8_WAIT_V(n) asm volatile("s_waitcnt vmcnt(" #n ")" ::: "memory")
; #define PG8_WAIT_L(n) asm volatile("s_waitcnt lgkmcnt(" #n ")" ::: "memory")
; #define PG8_BAR __builtin_amdgcn_s_barrier()
; #define PG8_SCHED __builtin_amdgcn_sched_barrier(0)
; template <class Epi, class Sched>
; __device__ __forceinline__ void gemm_phase(LAS unsigned char* lds, const Gemm g, const Sched& S, const Epi& E, const int tid) {
;     ...
;             PG8_WAIT_V(8); PG8_WAIT_L(0); PG8_BAR; PG8_MMA(1, 0, At, B0); PG8_MMA(1, 1, At, B1); PG8_BAR; PG8_SCHED;
;             PG8_LDB(B0, 1, 0); PG8_LDB(B1, 1, 1); PG8_SCHED; PG8_LDA(At, 1, 0); PG8_STAGE(PG8_SA(0, 1), a2 + hstepA, voffA);
;             PG8_WAIT_V(8); PG8_WAIT_L(0); PG8_BAR; PG8_MMA(0, 0, At, B0); PG8_MMA(0, 1, At, B1); PG8_BAR; PG8_SCHED;
	s_setprio 1
	s_waitcnt lgkmcnt(0)
	v_mfma_f32_16x16x32_bf16 v[62:65], v[140:143], v[186:189], v[62:65]
	v_mfma_f32_16x16x32_bf16 v[58:61], v[162:165], v[186:189], v[58:61]
	v_mfma_f32_16x16x32_bf16 v[46:49], v[140:143], v[194:197], v[46:49]
	v_mfma_f32_16x16x32_bf16 v[42:45], v[162:165], v[194:197], v[42:45]
	v_mfma_f32_16x16x32_bf16 v[30:33], v[140:143], v[204:207], v[30:33]
	v_mfma_f32_16x16x32_bf16 v[26:29], v[162:165], v[204:207], v[26:29]
	v_mfma_f32_16x16x32_bf16 v[14:17], v[140:143], v[212:215], v[14:17]
	v_mfma_f32_16x16x32_bf16 v[10:13], v[162:165], v[212:215], v[10:13]
	v_mfma_f32_16x16x32_bf16 v[62:65], v[158:161], v[190:193], v[62:65]
	v_mfma_f32_16x16x32_bf16 v[58:61], v[166:169], v[190:193], v[58:61]
	v_mfma_f32_16x16x32_bf16 v[46:49], v[158:161], v[198:201], v[46:49]
	v_mfma_f32_16x16x32_bf16 v[42:45], v[166:169], v[198:201], v[42:45]
	v_mfma_f32_16x16x32_bf16 v[30:33], v[158:161], v[208:211], v[30:33]
	v_mfma_f32_16x16x32_bf16 v[26:29], v[166:169], v[208:211], v[26:29]
	v_mfma_f32_16x16x32_bf16 v[14:17], v[158:161], v[216:219], v[14:17]
	v_mfma_f32_16x16x32_bf16 v[10:13], v[166:169], v[216:219], v[10:13]
	s_setprio 0
	s_setprio 1
	v_mfma_f32_16x16x32_bf16 v[54:57], v[170:173], v[186:189], v[54:57]
	v_mfma_f32_16x16x32_bf16 v[50:53], v[178:181], v[186:189], v[50:53]
	v_mfma_f32_16x16x32_bf16 v[38:41], v[170:173], v[194:197], v[38:41]
	v_mfma_f32_16x16x32_bf16 v[34:37], v[178:181], v[194:197], v[34:37]
	v_mfma_f32_16x16x32_bf16 v[22:25], v[170:173], v[204:207], v[22:25]
	v_mfma_f32_16x16x32_bf16 v[18:21], v[178:181], v[204:207], v[18:21]
	v_mfma_f32_16x16x32_bf16 v[6:9], v[170:173], v[212:215], v[6:9]
	v_mfma_f32_16x16x32_bf16 v[2:5], v[178:181], v[212:215], v[2:5]
	v_mfma_f32_16x16x32_bf16 v[54:57], v[174:177], v[190:193], v[54:57]
	v_mfma_f32_16x16x32_bf16 v[50:53], v[182:185], v[190:193], v[50:53]
	v_mfma_f32_16x16x32_bf16 v[38:41], v[174:177], v[198:201], v[38:41]
	v_mfma_f32_16x16x32_bf16 v[34:37], v[182:185], v[198:201], v[34:37]
	v_mfma_f32_16x16x32_bf16 v[22:25], v[174:177], v[208:211], v[22:25]
	v_mfma_f32_16x16x32_bf16 v[18:21], v[182:185], v[208:211], v[18:21]
	v_mfma_f32_16x16x32_bf16 v[6:9], v[174:177], v[216:219], v[6:9]
	v_mfma_f32_16x16x32_bf16 v[2:5], v[182:185], v[216:219], v[2:5]
	s_setprio 0
	s_barrier
	s_add_i32 s70, 0, 0x18000
	v_add_u32_e32 v144, s70, v147
	s_add_i32 s71, 0, 0x1c000
	ds_read_b128 v[140:143], v144
	ds_read_b128 v[158:161], v144 offset:1024
	ds_read_b128 v[162:165], v144 offset:2048
	ds_read_b128 v[166:169], v144 offset:3072
	v_add_u32_e32 v144, s71, v147
	ds_read_b128 v[170:173], v144
	ds_read_b128 v[174:177], v144 offset:1024
	ds_read_b128 v[178:181], v144 offset:2048
	ds_read_b128 v[182:185], v144 offset:3072
	s_add_u32 s14, s62, 0x80000
	s_addc_u32 s15, s63, 0
	s_mov_b32 m0, s47
	s_nop 0
	global_load_lds_dwordx4 v[224:225], off
	s_mov_b32 m0, s57
	s_nop 0
	global_load_lds_dwordx4 v[226:227], off
	s_mov_b32 m0, s64
	v_lshl_add_u64 v[228:229], s[14:15], 0, v[134:135]
	ds_read_b128 v[186:189], v157 offset:32768
	ds_read_b128 v[190:193], v157 offset:33792
	ds_read_b128 v[194:197], v157 offset:34816
	ds_read_b128 v[198:201], v157 offset:35840
	ds_read_b128 v[204:207], v157 offset:36864
	ds_read_b128 v[208:211], v157 offset:37888
	ds_read_b128 v[212:215], v157 offset:38912
	ds_read_b128 v[216:219], v157 offset:39936
	global_load_lds_dwordx4 v[228:229], off
	v_lshl_add_u64 v[228:229], s[14:15], 0, v[132:133]
	s_mov_b32 m0, s65
	s_nop 0
	global_load_lds_dwordx4 v[228:229], off
	s_waitcnt vmcnt(8)
	s_waitcnt lgkmcnt(0)
	s_barrier
	s_setprio 1
	s_waitcnt lgkmcnt(0)
	v_mfma_f32_16x16x32_bf16 v[126:129], v[140:143], v[186:189], v[126:129]
	v_mfma_f32_16x16x32_bf16 v[118:121], v[162:165], v[186:189], v[118:121]
	v_mfma_f32_16x16x32_bf16 v[110:113], v[140:143], v[194:197], v[110:113]
	v_mfma_f32_16x16x32_bf16 v[106:109], v[162:165], v[194:197], v[106:109]
	v_mfma_f32_16x16x32_bf16 v[94:97], v[140:143], v[204:207], v[94:97]
	v_mfma_f32_16x16x32_bf16 v[90:93], v[162:165], v[204:207], v[90:93]
	v_mfma_f32_16x16x32_bf16 v[78:81], v[140:143], v[212:215], v[78:81]
	v_mfma_f32_16x16x32_bf16 v[74:77], v[162:165], v[212:215], v[74:77]
	v_mfma_f32_16x16x32_bf16 v[126:129], v[158:161], v[190:193], v[126:129]
	v_mfma_f32_16x16x32_bf16 v[118:121], v[166:169], v[190:193], v[118:121]
	v_mfma_f32_16x16x32_bf16 v[110:113], v[158:161], v[198:201], v[110:113]
	v_mfma_f32_16x16x32_bf16 v[106:109], v[166:169], v[198:201], v[106:109]
	v_mfma_f32_16x16x32_bf16 v[94:97], v[158:161], v[208:211], v[94:97]
	v_mfma_f32_16x16x32_bf16 v[90:93], v[166:169], v[208:211], v[90:93]
	v_mfma_f32_16x16x32_bf16 v[78:81], v[158:161], v[216:219], v[78:81]
	v_mfma_f32_16x16x32_bf16 v[74:77], v[166:169], v[216:219], v[74:77]
	s_setprio 0
	s_setprio 1
	v_mfma_f32_16x16x32_bf16 v[122:125], v[170:173], v[186:189], v[122:125]
	v_mfma_f32_16x16x32_bf16 v[114:117], v[178:181], v[186:189], v[114:117]
	v_mfma_f32_16x16x32_bf16 v[102:105], v[170:173], v[194:197], v[102:105]
	v_mfma_f32_16x16x32_bf16 v[98:101], v[178:181], v[194:197], v[98:101]
	v_mfma_f32_16x16x32_bf16 v[86:89], v[170:173], v[204:207], v[86:89]
	v_mfma_f32_16x16x32_bf16 v[82:85], v[178:181], v[204:207], v[82:85]
	v_mfma_f32_16x16x32_bf16 v[70:73], v[170:173], v[212:215], v[70:73]
	v_mfma_f32_16x16x32_bf16 v[66:69], v[178:181], v[212:215], v[66:69]
	v_mfma_f32_16x16x32_bf16 v[122:125], v[174:177], v[190:193], v[122:125]
	v_mfma_f32_16x16x32_bf16 v[114:117], v[182:185], v[190:193], v[114:117]
	v_mfma_f32_16x16x32_bf16 v[102:105], v[174:177], v[198:201], v[102:105]
	v_mfma_f32_16x16x32_bf16 v[98:101], v[182:185], v[198:201], v[98:101]
	v_mfma_f32_16x16x32_bf16 v[86:89], v[174:177], v[208:211], v[86:89]
	v_mfma_f32_16x16x32_bf16 v[82:85], v[182:185], v[208:211], v[82:85]
	v_mfma_f32_16x16x32_bf16 v[70:73], v[174:177], v[216:219], v[70:73]
	v_mfma_f32_16x16x32_bf16 v[66:69], v[182:185], v[216:219], v[66:69]
	s_setprio 0
	s_barrier
; #define PG8_STAGE(bufoff, gbase, voff) do { _Pragma("unroll") for (int _i = 0; _i < 2; ++_i) \
;         __builtin_amdgcn_global_load_lds((const unsigned*)((const char*)(gbase) + (voff)[_i]), (LAS unsigned*)(lds + (bufoff) + ldsw + _i * 8192), 16, 0, 0); } while (0)
; #define PG8_LDA(dst, b, h) do { _Pragma("unroll") for (int m = 0; m < 4; ++m) _Pragma("unroll") for (int k = 0; k < 2; ++k) dst[m][k] = *(const LAS bf16x8*)(lds + PG8_SA(b, h) + aoff + m * 2048 + k * 1024); } while (0)
; #define PG8_MMA(ai, bj, At, Bt) do { __builtin_amdgcn_s_setprio(1); _Pragma("unroll") for (int m = 0; m < 4; ++m) _Pragma("unroll") for (int n = 0; n < 2; ++n) _Pragma("unroll") for (int k = 0; k < 2; ++k) \
;         acc[ai][bj][m][n] = __builtin_amdgcn_mfma_f32_16x16x32_bf16(Bt[n][k], At[m][k], acc[ai][bj][m][n], 0, 0, 0); __builtin_amdgcn_s_setprio(0); } while (0)
; #define PG8_WAIT_V(n) asm volatile("s_waitcnt vmcnt(" #n ")" ::: "memory")
; #define PG8_WAIT_L(n) asm volatile("s_waitcnt lgkmcnt(" #n ")" ::: "memory")
; #define PG8_BAR __builtin_amdgcn_s_barrier()
; #define PG8_SCHED __builtin_amdgcn_sched_barrier(0)
; template <class Epi, class Sched>
; __device__ __forceinline__ void gemm_phase(LAS unsigned char* lds, const Gemm g, const Sched& S, const Epi& E, const int tid) {
;     ...
;             PG8_LDA(At, 1, 1); PG8_STAGE(PG8_SB(1, 0), b3, voffB); PG8_STAGE(PG8_SB(1, 1), b3 + hstepB, voffB); PG8_STAGE(PG8_SA(1, 0), a3, voffA);
;             PG8_WAIT_V(8); PG8_WAIT_L(0); PG8_BAR; PG8_MMA(1, 0, At, B0); PG8_MMA(1, 1, At, B1); PG8_BAR; PG8_SCHED;
;         }
	s_add_i32 s14, s70, s46
	v_lshl_add_u64 v[220:221], v[220:221], 0, s[90:91]
	s_mov_b32 m0, s14
	ds_read_b128 v[186:189], v157 offset:49152
	ds_read_b128 v[190:193], v157 offset:50176
	ds_read_b128 v[194:197], v157 offset:51200
	ds_read_b128 v[198:201], v157 offset:52224
	ds_read_b128 v[204:207], v157 offset:53248
	ds_read_b128 v[208:211], v157 offset:54272
	ds_read_b128 v[212:215], v157 offset:55296
	ds_read_b128 v[216:219], v157 offset:56320
	global_load_lds_dwordx4 v[220:221], off
	s_add_i32 m0, s14, 0x2000
	s_add_u32 s14, s60, 0x80080
	v_lshl_add_u64 v[220:221], v[222:223], 0, s[90:91]
	s_addc_u32 s15, s61, 0
	s_add_i32 s60, s71, s46
	global_load_lds_dwordx4 v[220:221], off
	v_lshl_add_u64 v[220:221], s[14:15], 0, v[0:1]
	s_mov_b32 m0, s60
	s_nop 0
	global_load_lds_dwordx4 v[220:221], off
	v_lshl_add_u64 v[220:221], s[14:15], 0, v[130:131]
	s_add_i32 m0, s60, 0x2000
	s_nop 0
	global_load_lds_dwordx4 v[220:221], off
	v_lshl_add_u64 v[220:221], v[224:225], 0, s[90:91]
	s_mov_b32 m0, s66
	s_nop 0
	global_load_lds_dwordx4 v[220:221], off
	v_lshl_add_u64 v[220:221], v[226:227], 0, s[90:91]
	s_mov_b32 m0, s67
	s_nop 0
	global_load_lds_dwordx4 v[220:221], off
	s_waitcnt vmcnt(8)
	s_waitcnt lgkmcnt(0)
	s_barrier
	s_setprio 1
	s_waitcnt lgkmcnt(0)
	v_mfma_f32_16x16x32_bf16 v[62:65], v[140:143], v[186:189], v[62:65]
	v_mfma_f32_16x16x32_bf16 v[58:61], v[162:165], v[186:189], v[58:61]
	v_mfma_f32_16x16x32_bf16 v[46:49], v[140:143], v[194:197], v[46:49]
	v_mfma_f32_16x16x32_bf16 v[42:45], v[162:165], v[194:197], v[42:45]
	v_mfma_f32_16x16x32_bf16 v[30:33], v[140:143], v[204:207], v[30:33]
	v_mfma_f32_16x16x32_bf16 v[26:29], v[162:165], v[204:207], v[26:29]
	v_mfma_f32_16x16x32_bf16 v[14:17], v[140:143], v[212:215], v[14:17]
	v_mfma_f32_16x16x32_bf16 v[10:13], v[162:165], v[212:215], v[10:13]
	v_mfma_f32_16x16x32_bf16 v[62:65], v[158:161], v[190:193], v[62:65]
	v_mfma_f32_16x16x32_bf16 v[58:61], v[166:169], v[190:193], v[58:61]
	v_mfma_f32_16x16x32_bf16 v[46:49], v[158:161], v[198:201], v[46:49]
	v_mfma_f32_16x16x32_bf16 v[42:45], v[166:169], v[198:201], v[42:45]
	v_mfma_f32_16x16x32_bf16 v[30:33], v[158:161], v[208:211], v[30:33]
	v_mfma_f32_16x16x32_bf16 v[26:29], v[166:169], v[208:211], v[26:29]
	v_mfma_f32_16x16x32_bf16 v[14:17], v[158:161], v[216:219], v[14:17]
	v_mfma_f32_16x16x32_bf16 v[10:13], v[166:169], v[216:219], v[10:13]
	s_setprio 0
	s_setprio 1
	v_mfma_f32_16x16x32_bf16 v[54:57], v[170:173], v[186:189], v[54:57]
	v_mfma_f32_16x16x32_bf16 v[50:53], v[178:181], v[186:189], v[50:53]
	v_mfma_f32_16x16x32_bf16 v[38:41], v[170:173], v[194:197], v[38:41]
	v_mfma_f32_16x16x32_bf16 v[34:37], v[178:181], v[194:197], v[34:37]
	v_mfma_f32_16x16x32_bf16 v[22:25], v[170:173], v[204:207], v[22:25]
	v_mfma_f32_16x16x32_bf16 v[18:21], v[178:181], v[204:207], v[18:21]
	v_mfma_f32_16x16x32_bf16 v[6:9], v[170:173], v[212:215], v[6:9]
	v_mfma_f32_16x16x32_bf16 v[2:5], v[178:181], v[212:215], v[2:5]
	v_mfma_f32_16x16x32_bf16 v[54:57], v[174:177], v[190:193], v[54:57]
	v_mfma_f32_16x16x32_bf16 v[50:53], v[182:185], v[190:193], v[50:53]
	v_mfma_f32_16x16x32_bf16 v[38:41], v[174:177], v[198:201], v[38:41]
	v_mfma_f32_16x16x32_bf16 v[34:37], v[182:185], v[198:201], v[34:37]
	v_mfma_f32_16x16x32_bf16 v[22:25], v[174:177], v[208:211], v[22:25]
	v_mfma_f32_16x16x32_bf16 v[18:21], v[182:185], v[208:211], v[18:21]
	v_mfma_f32_16x16x32_bf16 v[6:9], v[174:177], v[216:219], v[6:9]
	v_mfma_f32_16x16x32_bf16 v[2:5], v[182:185], v[216:219], v[2:5]
	s_setprio 0
	s_barrier
	s_add_i32 s45, s45, 2
	s_add_u32 s69, s69, 0x100
	s_addc_u32 s44, s44, 0
	s_add_u32 s58, s58, 0x100
	s_addc_u32 s59, s59, 0
	s_cmp_gt_u32 s45, 29
	s_cbranch_scc0 .LBB1_87
	s_and_b64 vcc, exec, s[26:27]
	s_cbranch_vccz .LBB1_90
	s_barrier

; #define PG8_STAGE(bufoff, gbase, voff) do { _Pragma("unroll") for (int _i = 0; _i < 2; ++_i) \
;         __builtin_amdgcn_global_load_lds((const unsigned*)((const char*)(gbase) + (voff)[_i]), (LAS unsigned*)(lds + (bufoff) + ldsw + _i * 8192), 16, 0, 0); } while (0)
; #define PG8_LDA(dst, b, h) do { _Pragma("unroll") for (int m = 0; m < 4; ++m) _Pragma("unroll") for (int k = 0; k < 2; ++k) dst[m][k] = *(const LAS bf16x8*)(lds + PG8_SA(b, h) + aoff + m * 2048 + k * 1024); } while (0)
; #define PG8_LDB(dst, b, h) do { _Pragma("unroll") for (int n = 0; n < 2; ++n) _Pragma("unroll") for (int k = 0; k < 2; ++k) dst[n][k] = *(const LAS bf16x8*)(lds + PG8_SB(b, h) + boff + n * 2048 + k * 1024); } while (0)
; #define PG8_MMA(ai, bj, At, Bt) do { __builtin_amdgcn_s_setprio(1); _Pragma("unroll") for (int m = 0; m < 4; ++m) _Pragma("unroll") for (int n = 0; n < 2; ++n) _Pragma("unroll") for (int k = 0; k < 2; ++k) \
;         acc[ai][bj][m][n] = __builtin_amdgcn_mfma_f32_16x16x32_bf16(Bt[n][k], At[m][k], acc[ai][bj][m][n], 0, 0, 0); __builtin_amdgcn_s_setprio(0); } while (0)
; #define PG8_WAIT_V(n) asm volatile("s_waitcnt vmcnt(" #n ")" ::: "memory")
; #define PG8_WAIT_L(n) asm volatile("s_waitcnt lgkmcnt(" #n ")" ::: "memory")
; #define PG8_BAR __builtin_amdgcn_s_barrier()
; #define PG8_SCHED __builtin_amdgcn_sched_barrier(0)
; template <class Epi, class Sched>
; __device__ __forceinline__ void gemm_phase(LAS unsigned char* lds, const Gemm g, const Sched& S, const Epi& E, const int tid) {
;     ...
;             const char* a1 = cA + (size_t)(t + 1) * kstep;
;             const char* a2 = last ? nA : cA + (size_t)(t + 2) * kstep; const char* b2 = last ? nB : cB + (size_t)(t + 2) * kstep;
;             const char* a3 = a2 + kstep; const char* b3 = b2 + kstep;
;             PG8_LDB(B0, 0, 0); PG8_LDB(B1, 0, 1); PG8_SCHED; PG8_LDA(At, 0, 0); PG8_STAGE(PG8_SA(1, 1), a1 + hstepA, voffA);
;             PG8_WAIT_V(8); PG8_WAIT_L(0); PG8_BAR; PG8_MMA(0, 0, At, B0); PG8_MMA(0, 1, At, B1); PG8_BAR; PG8_SCHED;
;             PG8_LDA(At, 0, 1); PG8_STAGE(PG8_SB(0, 0), b2, voffB); PG8_STAGE(PG8_SB(0, 1), b2 + hstepB, voffB); PG8_STAGE(PG8_SA(0, 0), a2, voffA);
;             PG8_WAIT_V(8); PG8_WAIT_L(0); PG8_BAR; PG8_MMA(1, 0, At, B0); PG8_MMA(1, 1, At, B1); PG8_BAR; PG8_SCHED;
.LBB1_113:
	s_add_u32 s14, s64, 0xfff80080
	s_addc_u32 s15, s65, -1
	s_add_i32 s76, 0, 0x10000
	s_cmp_eq_u32 s45, 28
	s_cselect_b32 s69, s49, s15
	s_cselect_b32 s68, s61, s14
	s_cselect_b32 s67, s53, s44
	s_cselect_b32 s66, s74, s75
	s_add_i32 s77, 0, 0x14000
	v_add_u32_e32 v142, s76, v207
	v_add_u32_e32 v158, s77, v207
	ds_read_b128 v[130:133], v142
	ds_read_b128 v[134:137], v142 offset:1024
	ds_read_b128 v[138:141], v142 offset:2048
	ds_read_b128 v[142:145], v142 offset:3072
	ds_read_b128 v[146:149], v158
	ds_read_b128 v[150:153], v158 offset:1024
	ds_read_b128 v[154:157], v158 offset:2048
	ds_read_b128 v[158:161], v158 offset:3072
	v_lshl_add_u64 v[200:201], s[64:65], 0, v[186:187]
	s_add_i32 m0, s47, 0xc000
	ds_read_b128 v[162:165], v212
	ds_read_b128 v[166:169], v212 offset:1024
	ds_read_b128 v[170:173], v212 offset:2048
	ds_read_b128 v[174:177], v212 offset:3072
	ds_read_b128 v[188:191], v212 offset:4096
	ds_read_b128 v[192:195], v212 offset:5120
	ds_read_b128 v[196:199], v212 offset:6144
	ds_read_b128 v[214:217], v212 offset:7168
	global_load_lds_dwordx4 v[200:201], off
	v_lshl_add_u64 v[200:201], s[64:65], 0, v[184:185]
	s_add_i32 m0, s47, 0xe000
	s_nop 0
	global_load_lds_dwordx4 v[200:201], off
	s_waitcnt vmcnt(8)
	s_waitcnt lgkmcnt(0)
	s_barrier
	s_setprio 1
	s_waitcnt lgkmcnt(0)
	v_mfma_f32_16x16x32_bf16 v[126:129], v[130:133], v[162:165], v[126:129]
	v_mfma_f32_16x16x32_bf16 v[122:125], v[138:141], v[162:165], v[122:125]
	v_mfma_f32_16x16x32_bf16 v[110:113], v[130:133], v[170:173], v[110:113]
	v_mfma_f32_16x16x32_bf16 v[106:109], v[138:141], v[170:173], v[106:109]
	v_mfma_f32_16x16x32_bf16 v[94:97], v[130:133], v[188:191], v[94:97]
	v_mfma_f32_16x16x32_bf16 v[90:93], v[138:141], v[188:191], v[90:93]
	v_mfma_f32_16x16x32_bf16 v[78:81], v[130:133], v[196:199], v[78:81]
	v_mfma_f32_16x16x32_bf16 v[74:77], v[138:141], v[196:199], v[74:77]
	v_mfma_f32_16x16x32_bf16 v[126:129], v[134:137], v[166:169], v[126:129]
	v_mfma_f32_16x16x32_bf16 v[122:125], v[142:145], v[166:169], v[122:125]
	v_mfma_f32_16x16x32_bf16 v[110:113], v[134:137], v[174:177], v[110:113]
	v_mfma_f32_16x16x32_bf16 v[106:109], v[142:145], v[174:177], v[106:109]
	v_mfma_f32_16x16x32_bf16 v[94:97], v[134:137], v[192:195], v[94:97]
	v_mfma_f32_16x16x32_bf16 v[90:93], v[142:145], v[192:195], v[90:93]
	v_mfma_f32_16x16x32_bf16 v[78:81], v[134:137], v[214:217], v[78:81]
	v_mfma_f32_16x16x32_bf16 v[74:77], v[142:145], v[214:217], v[74:77]
	s_setprio 0
	s_setprio 1
	v_mfma_f32_16x16x32_bf16 v[118:121], v[146:149], v[162:165], v[118:121]
	v_mfma_f32_16x16x32_bf16 v[114:117], v[154:157], v[162:165], v[114:117]
	v_mfma_f32_16x16x32_bf16 v[102:105], v[146:149], v[170:173], v[102:105]
	v_mfma_f32_16x16x32_bf16 v[98:101], v[154:157], v[170:173], v[98:101]
	v_mfma_f32_16x16x32_bf16 v[86:89], v[146:149], v[188:191], v[86:89]
	v_mfma_f32_16x16x32_bf16 v[82:85], v[154:157], v[188:191], v[82:85]
	v_mfma_f32_16x16x32_bf16 v[70:73], v[146:149], v[196:199], v[70:73]
	v_mfma_f32_16x16x32_bf16 v[66:69], v[154:157], v[196:199], v[66:69]
	v_mfma_f32_16x16x32_bf16 v[118:121], v[150:153], v[166:169], v[118:121]
	v_mfma_f32_16x16x32_bf16 v[114:117], v[158:161], v[166:169], v[114:117]
	v_mfma_f32_16x16x32_bf16 v[102:105], v[150:153], v[174:177], v[102:105]
	v_mfma_f32_16x16x32_bf16 v[98:101], v[158:161], v[174:177], v[98:101]
	v_mfma_f32_16x16x32_bf16 v[86:89], v[150:153], v[192:195], v[86:89]
	v_mfma_f32_16x16x32_bf16 v[82:85], v[158:161], v[192:195], v[82:85]
	v_mfma_f32_16x16x32_bf16 v[70:73], v[150:153], v[214:217], v[70:73]
	v_mfma_f32_16x16x32_bf16 v[66:69], v[158:161], v[214:217], v[66:69]
	s_setprio 0
	s_barrier
	s_add_i32 s14, s76, s46
	v_lshl_add_u64 v[200:201], s[66:67], 0, v[0:1]
	s_mov_b32 m0, s14
	ds_read_b128 v[162:165], v212 offset:16384
	ds_read_b128 v[166:169], v212 offset:17408
	ds_read_b128 v[170:173], v212 offset:18432
	ds_read_b128 v[174:177], v212 offset:19456
	ds_read_b128 v[188:191], v212 offset:20480
	ds_read_b128 v[192:195], v212 offset:21504
	ds_read_b128 v[196:199], v212 offset:22528
	ds_read_b128 v[214:217], v212 offset:23552
	global_load_lds_dwordx4 v[200:201], off
	s_add_i32 m0, s14, 0x2000
	s_add_u32 s14, s66, 0x80000
	v_lshl_add_u64 v[204:205], s[66:67], 0, v[182:183]
	s_addc_u32 s15, s67, 0
	s_add_i32 s76, s77, s46
	global_load_lds_dwordx4 v[204:205], off
	v_lshl_add_u64 v[218:219], s[14:15], 0, v[0:1]
	s_mov_b32 m0, s76
	v_lshl_add_u64 v[220:221], s[68:69], 0, v[180:181]
	global_load_lds_dwordx4 v[218:219], off
	v_lshl_add_u64 v[218:219], s[14:15], 0, v[182:183]
	s_add_i32 m0, s76, 0x2000
	s_nop 0
	global_load_lds_dwordx4 v[218:219], off
	v_lshl_add_u64 v[218:219], s[68:69], 0, v[178:179]
	s_waitcnt vmcnt(6)
	s_waitcnt lgkmcnt(0)
	s_barrier
; #define PG8_STAGE(bufoff, gbase, voff) do { _Pragma("unroll") for (int _i = 0; _i < 2; ++_i) \
;         __builtin_amdgcn_global_load_lds((const unsigned*)((const char*)(gbase) + (voff)[_i]), (LAS unsigned*)(lds + (bufoff) + ldsw + _i * 8192), 16, 0, 0); } while (0)
; #define PG8_LDA(dst, b, h) do { _Pragma("unroll") for (int m = 0; m < 4; ++m) _Pragma("unroll") for (int k = 0; k < 2; ++k) dst[m][k] = *(const LAS bf16x8*)(lds + PG8_SA(b, h) + aoff + m * 2048 + k * 1024); } while (0)
; #define PG8_LDB(dst, b, h) do { _Pragma("unroll") for (int n = 0; n < 2; ++n) _Pragma("unroll") for (int k = 0; k < 2; ++k) dst[n][k] = *(const LAS bf16x8*)(lds + PG8_SB(b, h) + boff + n * 2048 + k * 1024); } while (0)
; #define PG8_MMA(ai, bj, At, Bt) do { __builtin_amdgcn_s_setprio(1); _Pragma("unroll") for (int m = 0; m < 4; ++m) _Pragma("unroll") for (int n = 0; n < 2; ++n) _Pragma("unroll") for (int k = 0; k < 2; ++k) \
;         acc[ai][bj][m][n] = __builtin_amdgcn_mfma_f32_16x16x32_bf16(Bt[n][k], At[m][k], acc[ai][bj][m][n], 0, 0, 0); __builtin_amdgcn_s_setprio(0); } while (0)
; #define PG8_WAIT_V(n) asm volatile("s_waitcnt vmcnt(" #n ")" ::: "memory")
; #define PG8_WAIT_L(n) asm volatile("s_waitcnt lgkmcnt(" #n ")" ::: "memory")
; #define PG8_BAR __builtin_amdgcn_s_barrier()
; #define PG8_SCHED __builtin_amdgcn_sched_barrier(0)
; template <class Epi, class Sched>
; __device__ __forceinline__ void gemm_phase(LAS unsigned char* lds, const Gemm g, const Sched& S, const Epi& E, const int tid) {
;     ...
;             PG8_WAIT_V(8); PG8_WAIT_L(0); PG8_BAR; PG8_MMA(1, 0, At, B0); PG8_MMA(1, 1, At, B1); PG8_BAR; PG8_SCHED;
;             PG8_LDB(B0, 1, 0); PG8_LDB(B1, 1, 1); PG8_SCHED; PG8_LDA(At, 1, 0); PG8_STAGE(PG8_SA(0, 1), a2 + hstepA, voffA);
;             PG8_WAIT_V(8); PG8_WAIT_L(0); PG8_BAR; PG8_MMA(0, 0, At, B0); PG8_MMA(0, 1, At, B1); PG8_BAR; PG8_SCHED;
	s_setprio 1
	s_waitcnt lgkmcnt(0)
	v_mfma_f32_16x16x32_bf16 v[62:65], v[130:133], v[162:165], v[62:65]
	v_mfma_f32_16x16x32_bf16 v[58:61], v[138:141], v[162:165], v[58:61]
	v_mfma_f32_16x16x32_bf16 v[46:49], v[130:133], v[170:173], v[46:49]
	v_mfma_f32_16x16x32_bf16 v[42:45], v[138:141], v[170:173], v[42:45]
	v_mfma_f32_16x16x32_bf16 v[30:33], v[130:133], v[188:191], v[30:33]
	v_mfma_f32_16x16x32_bf16 v[26:29], v[138:141], v[188:191], v[26:29]
	v_mfma_f32_16x16x32_bf16 v[14:17], v[130:133], v[196:199], v[14:17]
	v_mfma_f32_16x16x32_bf16 v[10:13], v[138:141], v[196:199], v[10:13]
	v_mfma_f32_16x16x32_bf16 v[62:65], v[134:137], v[166:169], v[62:65]
	v_mfma_f32_16x16x32_bf16 v[58:61], v[142:145], v[166:169], v[58:61]
	v_mfma_f32_16x16x32_bf16 v[46:49], v[134:137], v[174:177], v[46:49]
	v_mfma_f32_16x16x32_bf16 v[42:45], v[142:145], v[174:177], v[42:45]
	v_mfma_f32_16x16x32_bf16 v[30:33], v[134:137], v[192:195], v[30:33]
	v_mfma_f32_16x16x32_bf16 v[26:29], v[142:145], v[192:195], v[26:29]
	v_mfma_f32_16x16x32_bf16 v[14:17], v[134:137], v[214:217], v[14:17]
	v_mfma_f32_16x16x32_bf16 v[10:13], v[142:145], v[214:217], v[10:13]
	s_setprio 0
	s_setprio 1
	v_mfma_f32_16x16x32_bf16 v[54:57], v[146:149], v[162:165], v[54:57]
	v_mfma_f32_16x16x32_bf16 v[50:53], v[154:157], v[162:165], v[50:53]
	v_mfma_f32_16x16x32_bf16 v[38:41], v[146:149], v[170:173], v[38:41]
	v_mfma_f32_16x16x32_bf16 v[34:37], v[154:157], v[170:173], v[34:37]
	v_mfma_f32_16x16x32_bf16 v[22:25], v[146:149], v[188:191], v[22:25]
	v_mfma_f32_16x16x32_bf16 v[18:21], v[154:157], v[188:191], v[18:21]
	v_mfma_f32_16x16x32_bf16 v[6:9], v[146:149], v[196:199], v[6:9]
	v_mfma_f32_16x16x32_bf16 v[2:5], v[154:157], v[196:199], v[2:5]
	v_mfma_f32_16x16x32_bf16 v[54:57], v[150:153], v[166:169], v[54:57]
	v_mfma_f32_16x16x32_bf16 v[50:53], v[158:161], v[166:169], v[50:53]
	v_mfma_f32_16x16x32_bf16 v[38:41], v[150:153], v[174:177], v[38:41]
	v_mfma_f32_16x16x32_bf16 v[34:37], v[158:161], v[174:177], v[34:37]
	v_mfma_f32_16x16x32_bf16 v[22:25], v[150:153], v[192:195], v[22:25]
	v_mfma_f32_16x16x32_bf16 v[18:21], v[158:161], v[192:195], v[18:21]
	v_mfma_f32_16x16x32_bf16 v[6:9], v[150:153], v[214:217], v[6:9]
	v_mfma_f32_16x16x32_bf16 v[2:5], v[158:161], v[214:217], v[2:5]
	s_setprio 0
	s_barrier
	s_add_i32 s76, 0, 0x18000
	s_add_i32 s77, 0, 0x1c000
	v_add_u32_e32 v142, s76, v207
	v_add_u32_e32 v158, s77, v207
	ds_read_b128 v[130:133], v142
	ds_read_b128 v[134:137], v142 offset:1024
	ds_read_b128 v[138:141], v142 offset:2048
	ds_read_b128 v[142:145], v142 offset:3072
	ds_read_b128 v[146:149], v158
	ds_read_b128 v[150:153], v158 offset:1024
	ds_read_b128 v[154:157], v158 offset:2048
	ds_read_b128 v[158:161], v158 offset:3072
	s_add_u32 s14, s68, 0x80000
	s_addc_u32 s15, s69, 0
	s_mov_b32 m0, s47
	s_nop 0
	global_load_lds_dwordx4 v[218:219], off
	s_mov_b32 m0, s63
	s_nop 0
	global_load_lds_dwordx4 v[220:221], off
	s_mov_b32 m0, s84
	v_lshl_add_u64 v[222:223], s[14:15], 0, v[178:179]
	ds_read_b128 v[162:165], v212 offset:32768
	ds_read_b128 v[166:169], v212 offset:33792
	ds_read_b128 v[170:173], v212 offset:34816
	ds_read_b128 v[174:177], v212 offset:35840
	ds_read_b128 v[188:191], v212 offset:36864
	ds_read_b128 v[192:195], v212 offset:37888
	ds_read_b128 v[196:199], v212 offset:38912
	ds_read_b128 v[214:217], v212 offset:39936
	global_load_lds_dwordx4 v[222:223], off
	v_lshl_add_u64 v[222:223], s[14:15], 0, v[180:181]
	s_mov_b32 m0, s85
	s_nop 0
	global_load_lds_dwordx4 v[222:223], off
	s_waitcnt vmcnt(8)
	s_waitcnt lgkmcnt(0)
	s_barrier
	s_setprio 1
	s_waitcnt lgkmcnt(0)
	v_mfma_f32_16x16x32_bf16 v[126:129], v[130:133], v[162:165], v[126:129]
	v_mfma_f32_16x16x32_bf16 v[122:125], v[138:141], v[162:165], v[122:125]
	v_mfma_f32_16x16x32_bf16 v[110:113], v[130:133], v[170:173], v[110:113]
	v_mfma_f32_16x16x32_bf16 v[106:109], v[138:141], v[170:173], v[106:109]
	v_mfma_f32_16x16x32_bf16 v[94:97], v[130:133], v[188:191], v[94:97]
	v_mfma_f32_16x16x32_bf16 v[90:93], v[138:141], v[188:191], v[90:93]
	v_mfma_f32_16x16x32_bf16 v[78:81], v[130:133], v[196:199], v[78:81]
	v_mfma_f32_16x16x32_bf16 v[74:77], v[138:141], v[196:199], v[74:77]
	v_mfma_f32_16x16x32_bf16 v[126:129], v[134:137], v[166:169], v[126:129]
	v_mfma_f32_16x16x32_bf16 v[122:125], v[142:145], v[166:169], v[122:125]
	v_mfma_f32_16x16x32_bf16 v[110:113], v[134:137], v[174:177], v[110:113]
	v_mfma_f32_16x16x32_bf16 v[106:109], v[142:145], v[174:177], v[106:109]
	v_mfma_f32_16x16x32_bf16 v[94:97], v[134:137], v[192:195], v[94:97]
	v_mfma_f32_16x16x32_bf16 v[90:93], v[142:145], v[192:195], v[90:93]
	v_mfma_f32_16x16x32_bf16 v[78:81], v[134:137], v[214:217], v[78:81]
	v_mfma_f32_16x16x32_bf16 v[74:77], v[142:145], v[214:217], v[74:77]
	s_setprio 0
	s_setprio 1
	v_mfma_f32_16x16x32_bf16 v[118:121], v[146:149], v[162:165], v[118:121]
	v_mfma_f32_16x16x32_bf16 v[114:117], v[154:157], v[162:165], v[114:117]
	v_mfma_f32_16x16x32_bf16 v[102:105], v[146:149], v[170:173], v[102:105]
	v_mfma_f32_16x16x32_bf16 v[98:101], v[154:157], v[170:173], v[98:101]
	v_mfma_f32_16x16x32_bf16 v[86:89], v[146:149], v[188:191], v[86:89]
	v_mfma_f32_16x16x32_bf16 v[82:85], v[154:157], v[188:191], v[82:85]
	v_mfma_f32_16x16x32_bf16 v[70:73], v[146:149], v[196:199], v[70:73]
	v_mfma_f32_16x16x32_bf16 v[66:69], v[154:157], v[196:199], v[66:69]
	v_mfma_f32_16x16x32_bf16 v[118:121], v[150:153], v[166:169], v[118:121]
	v_mfma_f32_16x16x32_bf16 v[114:117], v[158:161], v[166:169], v[114:117]
	v_mfma_f32_16x16x32_bf16 v[102:105], v[150:153], v[174:177], v[102:105]
	v_mfma_f32_16x16x32_bf16 v[98:101], v[158:161], v[174:177], v[98:101]
	v_mfma_f32_16x16x32_bf16 v[86:89], v[150:153], v[192:195], v[86:89]
	v_mfma_f32_16x16x32_bf16 v[82:85], v[158:161], v[192:195], v[82:85]
	v_mfma_f32_16x16x32_bf16 v[70:73], v[150:153], v[214:217], v[70:73]
	v_mfma_f32_16x16x32_bf16 v[66:69], v[158:161], v[214:217], v[66:69]
	s_setprio 0
	s_barrier
; #define PG8_STAGE(bufoff, gbase, voff) do { _Pragma("unroll") for (int _i = 0; _i < 2; ++_i) \
;         __builtin_amdgcn_global_load_lds((const unsigned*)((const char*)(gbase) + (voff)[_i]), (LAS unsigned*)(lds + (bufoff) + ldsw + _i * 8192), 16, 0, 0); } while (0)
; #define PG8_LDA(dst, b, h) do { _Pragma("unroll") for (int m = 0; m < 4; ++m) _Pragma("unroll") for (int k = 0; k < 2; ++k) dst[m][k] = *(const LAS bf16x8*)(lds + PG8_SA(b, h) + aoff + m * 2048 + k * 1024); } while (0)
; #define PG8_MMA(ai, bj, At, Bt) do { __builtin_amdgcn_s_setprio(1); _Pragma("unroll") for (int m = 0; m < 4; ++m) _Pragma("unroll") for (int n = 0; n < 2; ++n) _Pragma("unroll") for (int k = 0; k < 2; ++k) \
;         acc[ai][bj][m][n] = __builtin_amdgcn_mfma_f32_16x16x32_bf16(Bt[n][k], At[m][k], acc[ai][bj][m][n], 0, 0, 0); __builtin_amdgcn_s_setprio(0); } while (0)
; #define PG8_WAIT_V(n) asm volatile("s_waitcnt vmcnt(" #n ")" ::: "memory")
; #define PG8_WAIT_L(n) asm volatile("s_waitcnt lgkmcnt(" #n ")" ::: "memory")
; #define PG8_BAR __builtin_amdgcn_s_barrier()
; #define PG8_SCHED __builtin_amdgcn_sched_barrier(0)
; template <class Epi, class Sched>
; __device__ __forceinline__ void gemm_phase(LAS unsigned char* lds, const Gemm g, const Sched& S, const Epi& E, const int tid) {
;     ...
;             PG8_LDA(At, 1, 1); PG8_STAGE(PG8_SB(1, 0), b3, voffB); PG8_STAGE(PG8_SB(1, 1), b3 + hstepB, voffB); PG8_STAGE(PG8_SA(1, 0), a3, voffA);
;             PG8_WAIT_V(8); PG8_WAIT_L(0); PG8_BAR; PG8_MMA(1, 0, At, B0); PG8_MMA(1, 1, At, B1); PG8_BAR; PG8_SCHED;
;         }
	s_add_i32 s14, s76, s46
	v_lshl_add_u64 v[200:201], v[200:201], 0, s[90:91]
	s_mov_b32 m0, s14
	ds_read_b128 v[162:165], v212 offset:49152
	ds_read_b128 v[166:169], v212 offset:50176
	ds_read_b128 v[170:173], v212 offset:51200
	ds_read_b128 v[174:177], v212 offset:52224
	ds_read_b128 v[188:191], v212 offset:53248
	ds_read_b128 v[192:195], v212 offset:54272
	ds_read_b128 v[196:199], v212 offset:55296
	ds_read_b128 v[214:217], v212 offset:56320
	global_load_lds_dwordx4 v[200:201], off
	s_add_i32 m0, s14, 0x2000
	s_add_u32 s14, s66, 0x80080
	v_lshl_add_u64 v[200:201], v[204:205], 0, s[90:91]
	s_addc_u32 s15, s67, 0
	s_add_i32 s66, s77, s46
	global_load_lds_dwordx4 v[200:201], off
	v_lshl_add_u64 v[200:201], s[14:15], 0, v[0:1]
	s_mov_b32 m0, s66
	s_nop 0
	global_load_lds_dwordx4 v[200:201], off
	v_lshl_add_u64 v[200:201], s[14:15], 0, v[182:183]
	s_add_i32 m0, s66, 0x2000
	s_nop 0
	global_load_lds_dwordx4 v[200:201], off
	v_lshl_add_u64 v[200:201], v[218:219], 0, s[90:91]
	s_mov_b32 m0, s72
	s_nop 0
	global_load_lds_dwordx4 v[200:201], off
	v_lshl_add_u64 v[200:201], v[220:221], 0, s[90:91]
	s_mov_b32 m0, s73
	s_nop 0
	global_load_lds_dwordx4 v[200:201], off
	s_waitcnt vmcnt(8)
	s_waitcnt lgkmcnt(0)
	s_barrier
	s_setprio 1
	s_waitcnt lgkmcnt(0)
	v_mfma_f32_16x16x32_bf16 v[62:65], v[130:133], v[162:165], v[62:65]
	v_mfma_f32_16x16x32_bf16 v[58:61], v[138:141], v[162:165], v[58:61]
	v_mfma_f32_16x16x32_bf16 v[46:49], v[130:133], v[170:173], v[46:49]
	v_mfma_f32_16x16x32_bf16 v[42:45], v[138:141], v[170:173], v[42:45]
	v_mfma_f32_16x16x32_bf16 v[30:33], v[130:133], v[188:191], v[30:33]
	v_mfma_f32_16x16x32_bf16 v[26:29], v[138:141], v[188:191], v[26:29]
	v_mfma_f32_16x16x32_bf16 v[14:17], v[130:133], v[196:199], v[14:17]
	v_mfma_f32_16x16x32_bf16 v[10:13], v[138:141], v[196:199], v[10:13]
	v_mfma_f32_16x16x32_bf16 v[62:65], v[134:137], v[166:169], v[62:65]
	v_mfma_f32_16x16x32_bf16 v[58:61], v[142:145], v[166:169], v[58:61]
	v_mfma_f32_16x16x32_bf16 v[46:49], v[134:137], v[174:177], v[46:49]
	v_mfma_f32_16x16x32_bf16 v[42:45], v[142:145], v[174:177], v[42:45]
	v_mfma_f32_16x16x32_bf16 v[30:33], v[134:137], v[192:195], v[30:33]
	v_mfma_f32_16x16x32_bf16 v[26:29], v[142:145], v[192:195], v[26:29]
	v_mfma_f32_16x16x32_bf16 v[14:17], v[134:137], v[214:217], v[14:17]
	v_mfma_f32_16x16x32_bf16 v[10:13], v[142:145], v[214:217], v[10:13]
	s_setprio 0
	s_setprio 1
	v_mfma_f32_16x16x32_bf16 v[54:57], v[146:149], v[162:165], v[54:57]
	v_mfma_f32_16x16x32_bf16 v[50:53], v[154:157], v[162:165], v[50:53]
	v_mfma_f32_16x16x32_bf16 v[38:41], v[146:149], v[170:173], v[38:41]
	v_mfma_f32_16x16x32_bf16 v[34:37], v[154:157], v[170:173], v[34:37]
	v_mfma_f32_16x16x32_bf16 v[22:25], v[146:149], v[188:191], v[22:25]
	v_mfma_f32_16x16x32_bf16 v[18:21], v[154:157], v[188:191], v[18:21]
	v_mfma_f32_16x16x32_bf16 v[6:9], v[146:149], v[196:199], v[6:9]
	v_mfma_f32_16x16x32_bf16 v[2:5], v[154:157], v[196:199], v[2:5]
	v_mfma_f32_16x16x32_bf16 v[54:57], v[150:153], v[166:169], v[54:57]
	v_mfma_f32_16x16x32_bf16 v[50:53], v[158:161], v[166:169], v[50:53]
	v_mfma_f32_16x16x32_bf16 v[38:41], v[150:153], v[174:177], v[38:41]
	v_mfma_f32_16x16x32_bf16 v[34:37], v[158:161], v[174:177], v[34:37]
	v_mfma_f32_16x16x32_bf16 v[22:25], v[150:153], v[192:195], v[22:25]
	v_mfma_f32_16x16x32_bf16 v[18:21], v[158:161], v[192:195], v[18:21]
	v_mfma_f32_16x16x32_bf16 v[6:9], v[150:153], v[214:217], v[6:9]
	v_mfma_f32_16x16x32_bf16 v[2:5], v[158:161], v[214:217], v[2:5]
	s_setprio 0
	s_barrier
	s_add_i32 s45, s45, 2
	s_add_u32 s75, s75, 0x100
	s_addc_u32 s44, s44, 0
	s_add_u32 s64, s64, 0x100
	s_addc_u32 s65, s65, 0
	s_cmp_gt_u32 s45, 29
	s_cbranch_scc0 .LBB1_113
	s_and_b64 vcc, exec, s[42:43]
	s_cbranch_vccz .LBB1_116
	s_barrier

; #define PG8_STAGE(bufoff, gbase, voff) do { _Pragma("unroll") for (int _i = 0; _i < 2; ++_i) \
;         __builtin_amdgcn_global_load_lds((const unsigned*)((const char*)(gbase) + (voff)[_i]), (LAS unsigned*)(lds + (bufoff) + ldsw + _i * 8192), 16, 0, 0); } while (0)
; #define PG8_LDA(dst, b, h) do { _Pragma("unroll") for (int m = 0; m < 4; ++m) _Pragma("unroll") for (int k = 0; k < 2; ++k) dst[m][k] = *(const LAS bf16x8*)(lds + PG8_SA(b, h) + aoff + m * 2048 + k * 1024); } while (0)
; #define PG8_LDB(dst, b, h) do { _Pragma("unroll") for (int n = 0; n < 2; ++n) _Pragma("unroll") for (int k = 0; k < 2; ++k) dst[n][k] = *(const LAS bf16x8*)(lds + PG8_SB(b, h) + boff + n * 2048 + k * 1024); } while (0)
; #define PG8_MMA(ai, bj, At, Bt) do { __builtin_amdgcn_s_setprio(1); _Pragma("unroll") for (int m = 0; m < 4; ++m) _Pragma("unroll") for (int n = 0; n < 2; ++n) _Pragma("unroll") for (int k = 0; k < 2; ++k) \
;         acc[ai][bj][m][n] = __builtin_amdgcn_mfma_f32_16x16x32_bf16(Bt[n][k], At[m][k], acc[ai][bj][m][n], 0, 0, 0); __builtin_amdgcn_s_setprio(0); } while (0)
; #define PG8_WAIT_V(n) asm volatile("s_waitcnt vmcnt(" #n ")" ::: "memory")
; #define PG8_WAIT_L(n) asm volatile("s_waitcnt lgkmcnt(" #n ")" ::: "memory")
; #define PG8_BAR __builtin_amdgcn_s_barrier()
; #define PG8_SCHED __builtin_amdgcn_sched_barrier(0)
; template <class Epi, class Sched>
; __device__ __forceinline__ void gemm_phase(LAS unsigned char* lds, const Gemm g, const Sched& S, const Epi& E, const int tid) {
;     ...
;             const char* a1 = cA + (size_t)(t + 1) * kstep;
;             const char* a2 = last ? nA : cA + (size_t)(t + 2) * kstep; const char* b2 = last ? nB : cB + (size_t)(t + 2) * kstep;
;             const char* a3 = a2 + kstep; const char* b3 = b2 + kstep;
;             PG8_LDB(B0, 0, 0); PG8_LDB(B1, 0, 1); PG8_SCHED; PG8_LDA(At, 0, 0); PG8_STAGE(PG8_SA(1, 1), a1 + hstepA, voffA);
;             PG8_WAIT_V(8); PG8_WAIT_L(0); PG8_BAR; PG8_MMA(0, 0, At, B0); PG8_MMA(0, 1, At, B1); PG8_BAR; PG8_SCHED;
;             PG8_LDA(At, 0, 1); PG8_STAGE(PG8_SB(0, 0), b2, voffB); PG8_STAGE(PG8_SB(0, 1), b2 + hstepB, voffB); PG8_STAGE(PG8_SA(0, 0), a2, voffA);
;             PG8_WAIT_V(8); PG8_WAIT_L(0); PG8_BAR; PG8_MMA(1, 0, At, B0); PG8_MMA(1, 1, At, B1); PG8_BAR; PG8_SCHED;
.LBB1_156:
	s_add_u32 s40, s60, 0x100
	s_addc_u32 s41, s61, 0
	s_add_i32 s49, 0, 0x10000
	s_cmp_eq_u32 s45, 12
	s_cselect_b32 s65, s57, s41
	s_cselect_b32 s64, s56, s40
	s_cselect_b32 s63, s14, s44
	s_cselect_b32 s62, s15, s43
	s_add_i32 s53, 0, 0x14000
	v_add_u32_e32 v142, s49, v231
	v_add_u32_e32 v158, s53, v231
	ds_read_b128 v[130:133], v142
	ds_read_b128 v[134:137], v142 offset:1024
	ds_read_b128 v[138:141], v142 offset:2048
	ds_read_b128 v[142:145], v142 offset:3072
	ds_read_b128 v[146:149], v158
	ds_read_b128 v[150:153], v158 offset:1024
	ds_read_b128 v[154:157], v158 offset:2048
	ds_read_b128 v[158:161], v158 offset:3072
	v_lshl_add_u64 v[194:195], s[60:61], 0, v[214:215]
	s_add_i32 m0, s47, 0xc000
	ds_read_b128 v[162:165], v236
	ds_read_b128 v[166:169], v236 offset:1024
	ds_read_b128 v[170:173], v236 offset:2048
	ds_read_b128 v[174:177], v236 offset:3072
	ds_read_b128 v[178:181], v236 offset:4096
	ds_read_b128 v[182:185], v236 offset:5120
	ds_read_b128 v[186:189], v236 offset:6144
	ds_read_b128 v[190:193], v236 offset:7168
	global_load_lds_dwordx4 v[194:195], off
	v_lshl_add_u64 v[194:195], s[60:61], 0, v[212:213]
	s_add_i32 m0, s47, 0xe000
	s_nop 0
	global_load_lds_dwordx4 v[194:195], off
	s_waitcnt vmcnt(8)
	s_waitcnt lgkmcnt(0)
	s_barrier
	s_setprio 1
	s_waitcnt lgkmcnt(0)
	v_mfma_f32_16x16x32_bf16 v[126:129], v[130:133], v[162:165], v[126:129]
	v_mfma_f32_16x16x32_bf16 v[122:125], v[138:141], v[162:165], v[122:125]
	v_mfma_f32_16x16x32_bf16 v[118:121], v[130:133], v[170:173], v[118:121]
	v_mfma_f32_16x16x32_bf16 v[114:117], v[138:141], v[170:173], v[114:117]
	v_mfma_f32_16x16x32_bf16 v[110:113], v[130:133], v[178:181], v[110:113]
	v_mfma_f32_16x16x32_bf16 v[106:109], v[138:141], v[178:181], v[106:109]
	v_mfma_f32_16x16x32_bf16 v[102:105], v[130:133], v[186:189], v[102:105]
	v_mfma_f32_16x16x32_bf16 v[98:101], v[138:141], v[186:189], v[98:101]
	v_mfma_f32_16x16x32_bf16 v[126:129], v[134:137], v[166:169], v[126:129]
	v_mfma_f32_16x16x32_bf16 v[122:125], v[142:145], v[166:169], v[122:125]
	v_mfma_f32_16x16x32_bf16 v[118:121], v[134:137], v[174:177], v[118:121]
	v_mfma_f32_16x16x32_bf16 v[114:117], v[142:145], v[174:177], v[114:117]
	v_mfma_f32_16x16x32_bf16 v[110:113], v[134:137], v[182:185], v[110:113]
	v_mfma_f32_16x16x32_bf16 v[106:109], v[142:145], v[182:185], v[106:109]
	v_mfma_f32_16x16x32_bf16 v[102:105], v[134:137], v[190:193], v[102:105]
	v_mfma_f32_16x16x32_bf16 v[98:101], v[142:145], v[190:193], v[98:101]
	s_setprio 0
	s_setprio 1
	v_mfma_f32_16x16x32_bf16 v[94:97], v[146:149], v[162:165], v[94:97]
	v_mfma_f32_16x16x32_bf16 v[90:93], v[154:157], v[162:165], v[90:93]
	v_mfma_f32_16x16x32_bf16 v[86:89], v[146:149], v[170:173], v[86:89]
	v_mfma_f32_16x16x32_bf16 v[82:85], v[154:157], v[170:173], v[82:85]
	v_mfma_f32_16x16x32_bf16 v[78:81], v[146:149], v[178:181], v[78:81]
	v_mfma_f32_16x16x32_bf16 v[74:77], v[154:157], v[178:181], v[74:77]
	v_mfma_f32_16x16x32_bf16 v[70:73], v[146:149], v[186:189], v[70:73]
	v_mfma_f32_16x16x32_bf16 v[66:69], v[154:157], v[186:189], v[66:69]
	v_mfma_f32_16x16x32_bf16 v[94:97], v[150:153], v[166:169], v[94:97]
	v_mfma_f32_16x16x32_bf16 v[90:93], v[158:161], v[166:169], v[90:93]
	v_mfma_f32_16x16x32_bf16 v[86:89], v[150:153], v[174:177], v[86:89]
	v_mfma_f32_16x16x32_bf16 v[82:85], v[158:161], v[174:177], v[82:85]
	v_mfma_f32_16x16x32_bf16 v[78:81], v[150:153], v[182:185], v[78:81]
	v_mfma_f32_16x16x32_bf16 v[74:77], v[158:161], v[182:185], v[74:77]
	v_mfma_f32_16x16x32_bf16 v[70:73], v[150:153], v[190:193], v[70:73]
	v_mfma_f32_16x16x32_bf16 v[66:69], v[158:161], v[190:193], v[66:69]
	s_setprio 0
	s_barrier
	s_add_i32 s49, s49, s46
	v_lshl_add_u64 v[194:195], s[62:63], 0, v[206:207]
	s_mov_b32 m0, s49
	ds_read_b128 v[162:165], v236 offset:16384
	ds_read_b128 v[166:169], v236 offset:17408
	ds_read_b128 v[170:173], v236 offset:18432
	ds_read_b128 v[174:177], v236 offset:19456
	ds_read_b128 v[178:181], v236 offset:20480
	ds_read_b128 v[182:185], v236 offset:21504
	ds_read_b128 v[186:189], v236 offset:22528
	ds_read_b128 v[190:193], v236 offset:23552
	global_load_lds_dwordx4 v[194:195], off
	s_add_i32 m0, s49, 0x2000
	s_add_u32 s60, s62, 0x40000
	v_lshl_add_u64 v[196:197], s[62:63], 0, v[210:211]
	s_addc_u32 s61, s63, 0
	s_add_i32 s49, s53, s46
	global_load_lds_dwordx4 v[196:197], off
	v_lshl_add_u64 v[198:199], s[60:61], 0, v[206:207]
	s_mov_b32 m0, s49
	v_lshl_add_u64 v[200:201], s[64:65], 0, v[208:209]
	global_load_lds_dwordx4 v[198:199], off
	v_lshl_add_u64 v[198:199], s[60:61], 0, v[210:211]
	s_add_i32 m0, s49, 0x2000
	s_nop 0
	global_load_lds_dwordx4 v[198:199], off
	v_lshl_add_u64 v[198:199], s[64:65], 0, v[204:205]
	s_waitcnt vmcnt(6)
	s_waitcnt lgkmcnt(0)
	s_barrier
; #define PG8_STAGE(bufoff, gbase, voff) do { _Pragma("unroll") for (int _i = 0; _i < 2; ++_i) \
;         __builtin_amdgcn_global_load_lds((const unsigned*)((const char*)(gbase) + (voff)[_i]), (LAS unsigned*)(lds + (bufoff) + ldsw + _i * 8192), 16, 0, 0); } while (0)
; #define PG8_LDA(dst, b, h) do { _Pragma("unroll") for (int m = 0; m < 4; ++m) _Pragma("unroll") for (int k = 0; k < 2; ++k) dst[m][k] = *(const LAS bf16x8*)(lds + PG8_SA(b, h) + aoff + m * 2048 + k * 1024); } while (0)
; #define PG8_LDB(dst, b, h) do { _Pragma("unroll") for (int n = 0; n < 2; ++n) _Pragma("unroll") for (int k = 0; k < 2; ++k) dst[n][k] = *(const LAS bf16x8*)(lds + PG8_SB(b, h) + boff + n * 2048 + k * 1024); } while (0)
; #define PG8_MMA(ai, bj, At, Bt) do { __builtin_amdgcn_s_setprio(1); _Pragma("unroll") for (int m = 0; m < 4; ++m) _Pragma("unroll") for (int n = 0; n < 2; ++n) _Pragma("unroll") for (int k = 0; k < 2; ++k) \
;         acc[ai][bj][m][n] = __builtin_amdgcn_mfma_f32_16x16x32_bf16(Bt[n][k], At[m][k], acc[ai][bj][m][n], 0, 0, 0); __builtin_amdgcn_s_setprio(0); } while (0)
; #define PG8_WAIT_V(n) asm volatile("s_waitcnt vmcnt(" #n ")" ::: "memory")
; #define PG8_WAIT_L(n) asm volatile("s_waitcnt lgkmcnt(" #n ")" ::: "memory")
; #define PG8_BAR __builtin_amdgcn_s_barrier()
; #define PG8_SCHED __builtin_amdgcn_sched_barrier(0)
; template <class Epi, class Sched>
; __device__ __forceinline__ void gemm_phase(LAS unsigned char* lds, const Gemm g, const Sched& S, const Epi& E, const int tid) {
;     ...
;             PG8_WAIT_V(8); PG8_WAIT_L(0); PG8_BAR; PG8_MMA(1, 0, At, B0); PG8_MMA(1, 1, At, B1); PG8_BAR; PG8_SCHED;
;             PG8_LDB(B0, 1, 0); PG8_LDB(B1, 1, 1); PG8_SCHED; PG8_LDA(At, 1, 0); PG8_STAGE(PG8_SA(0, 1), a2 + hstepA, voffA);
;             PG8_WAIT_V(8); PG8_WAIT_L(0); PG8_BAR; PG8_MMA(0, 0, At, B0); PG8_MMA(0, 1, At, B1); PG8_BAR; PG8_SCHED;
	s_setprio 1
	s_waitcnt lgkmcnt(0)
	v_mfma_f32_16x16x32_bf16 v[62:65], v[130:133], v[162:165], v[62:65]
	v_mfma_f32_16x16x32_bf16 v[58:61], v[138:141], v[162:165], v[58:61]
	v_mfma_f32_16x16x32_bf16 v[54:57], v[130:133], v[170:173], v[54:57]
	v_mfma_f32_16x16x32_bf16 v[50:53], v[138:141], v[170:173], v[50:53]
	v_mfma_f32_16x16x32_bf16 v[46:49], v[130:133], v[178:181], v[46:49]
	v_mfma_f32_16x16x32_bf16 v[42:45], v[138:141], v[178:181], v[42:45]
	v_mfma_f32_16x16x32_bf16 v[38:41], v[130:133], v[186:189], v[38:41]
	v_mfma_f32_16x16x32_bf16 v[34:37], v[138:141], v[186:189], v[34:37]
	v_mfma_f32_16x16x32_bf16 v[62:65], v[134:137], v[166:169], v[62:65]
	v_mfma_f32_16x16x32_bf16 v[58:61], v[142:145], v[166:169], v[58:61]
	v_mfma_f32_16x16x32_bf16 v[54:57], v[134:137], v[174:177], v[54:57]
	v_mfma_f32_16x16x32_bf16 v[50:53], v[142:145], v[174:177], v[50:53]
	v_mfma_f32_16x16x32_bf16 v[46:49], v[134:137], v[182:185], v[46:49]
	v_mfma_f32_16x16x32_bf16 v[42:45], v[142:145], v[182:185], v[42:45]
	v_mfma_f32_16x16x32_bf16 v[38:41], v[134:137], v[190:193], v[38:41]
	v_mfma_f32_16x16x32_bf16 v[34:37], v[142:145], v[190:193], v[34:37]
	s_setprio 0
	s_setprio 1
	v_mfma_f32_16x16x32_bf16 v[30:33], v[146:149], v[162:165], v[30:33]
	v_mfma_f32_16x16x32_bf16 v[26:29], v[154:157], v[162:165], v[26:29]
	v_mfma_f32_16x16x32_bf16 v[22:25], v[146:149], v[170:173], v[22:25]
	v_mfma_f32_16x16x32_bf16 v[18:21], v[154:157], v[170:173], v[18:21]
	v_mfma_f32_16x16x32_bf16 v[14:17], v[146:149], v[178:181], v[14:17]
	v_mfma_f32_16x16x32_bf16 v[10:13], v[154:157], v[178:181], v[10:13]
	v_mfma_f32_16x16x32_bf16 v[6:9], v[146:149], v[186:189], v[6:9]
	v_mfma_f32_16x16x32_bf16 v[2:5], v[154:157], v[186:189], v[2:5]
	v_mfma_f32_16x16x32_bf16 v[30:33], v[150:153], v[166:169], v[30:33]
	v_mfma_f32_16x16x32_bf16 v[26:29], v[158:161], v[166:169], v[26:29]
	v_mfma_f32_16x16x32_bf16 v[22:25], v[150:153], v[174:177], v[22:25]
	v_mfma_f32_16x16x32_bf16 v[18:21], v[158:161], v[174:177], v[18:21]
	v_mfma_f32_16x16x32_bf16 v[14:17], v[150:153], v[182:185], v[14:17]
	v_mfma_f32_16x16x32_bf16 v[10:13], v[158:161], v[182:185], v[10:13]
	v_mfma_f32_16x16x32_bf16 v[6:9], v[150:153], v[190:193], v[6:9]
	v_mfma_f32_16x16x32_bf16 v[2:5], v[158:161], v[190:193], v[2:5]
	s_setprio 0
	s_barrier
	s_add_i32 s49, 0, 0x18000
	s_add_i32 s53, 0, 0x1c000
	v_add_u32_e32 v142, s49, v231
	v_add_u32_e32 v158, s53, v231
	ds_read_b128 v[130:133], v142
	ds_read_b128 v[134:137], v142 offset:1024
	ds_read_b128 v[138:141], v142 offset:2048
	ds_read_b128 v[142:145], v142 offset:3072
	ds_read_b128 v[146:149], v158
	ds_read_b128 v[150:153], v158 offset:1024
	ds_read_b128 v[154:157], v158 offset:2048
	ds_read_b128 v[158:161], v158 offset:3072
	s_add_u32 s60, s64, 0x300000
	s_addc_u32 s61, s65, 0
	s_mov_b32 m0, s47
	s_nop 0
	global_load_lds_dwordx4 v[198:199], off
	s_mov_b32 m0, s66
	s_nop 0
	global_load_lds_dwordx4 v[200:201], off
	s_mov_b32 m0, s67
	v_lshl_add_u64 v[216:217], s[60:61], 0, v[204:205]
	ds_read_b128 v[162:165], v236 offset:32768
	ds_read_b128 v[166:169], v236 offset:33792
	ds_read_b128 v[170:173], v236 offset:34816
	ds_read_b128 v[174:177], v236 offset:35840
	ds_read_b128 v[178:181], v236 offset:36864
	ds_read_b128 v[182:185], v236 offset:37888
	ds_read_b128 v[186:189], v236 offset:38912
	ds_read_b128 v[190:193], v236 offset:39936
	global_load_lds_dwordx4 v[216:217], off
	v_lshl_add_u64 v[216:217], s[60:61], 0, v[208:209]
	s_mov_b32 m0, s68
	s_nop 0
	global_load_lds_dwordx4 v[216:217], off
	s_waitcnt vmcnt(8)
	s_waitcnt lgkmcnt(0)
	s_barrier
	s_setprio 1
	s_waitcnt lgkmcnt(0)
	v_mfma_f32_16x16x32_bf16 v[126:129], v[130:133], v[162:165], v[126:129]
	v_mfma_f32_16x16x32_bf16 v[122:125], v[138:141], v[162:165], v[122:125]
	v_mfma_f32_16x16x32_bf16 v[118:121], v[130:133], v[170:173], v[118:121]
	v_mfma_f32_16x16x32_bf16 v[114:117], v[138:141], v[170:173], v[114:117]
	v_mfma_f32_16x16x32_bf16 v[110:113], v[130:133], v[178:181], v[110:113]
	v_mfma_f32_16x16x32_bf16 v[106:109], v[138:141], v[178:181], v[106:109]
	v_mfma_f32_16x16x32_bf16 v[102:105], v[130:133], v[186:189], v[102:105]
	v_mfma_f32_16x16x32_bf16 v[98:101], v[138:141], v[186:189], v[98:101]
	v_mfma_f32_16x16x32_bf16 v[126:129], v[134:137], v[166:169], v[126:129]
	v_mfma_f32_16x16x32_bf16 v[122:125], v[142:145], v[166:169], v[122:125]
	v_mfma_f32_16x16x32_bf16 v[118:121], v[134:137], v[174:177], v[118:121]
	v_mfma_f32_16x16x32_bf16 v[114:117], v[142:145], v[174:177], v[114:117]
	v_mfma_f32_16x16x32_bf16 v[110:113], v[134:137], v[182:185], v[110:113]
	v_mfma_f32_16x16x32_bf16 v[106:109], v[142:145], v[182:185], v[106:109]
	v_mfma_f32_16x16x32_bf16 v[102:105], v[134:137], v[190:193], v[102:105]
	v_mfma_f32_16x16x32_bf16 v[98:101], v[142:145], v[190:193], v[98:101]
	s_setprio 0
	s_setprio 1
	v_mfma_f32_16x16x32_bf16 v[94:97], v[146:149], v[162:165], v[94:97]
	v_mfma_f32_16x16x32_bf16 v[90:93], v[154:157], v[162:165], v[90:93]
	v_mfma_f32_16x16x32_bf16 v[86:89], v[146:149], v[170:173], v[86:89]
	v_mfma_f32_16x16x32_bf16 v[82:85], v[154:157], v[170:173], v[82:85]
	v_mfma_f32_16x16x32_bf16 v[78:81], v[146:149], v[178:181], v[78:81]
	v_mfma_f32_16x16x32_bf16 v[74:77], v[154:157], v[178:181], v[74:77]
	v_mfma_f32_16x16x32_bf16 v[70:73], v[146:149], v[186:189], v[70:73]
	v_mfma_f32_16x16x32_bf16 v[66:69], v[154:157], v[186:189], v[66:69]
	v_mfma_f32_16x16x32_bf16 v[94:97], v[150:153], v[166:169], v[94:97]
	v_mfma_f32_16x16x32_bf16 v[90:93], v[158:161], v[166:169], v[90:93]
	v_mfma_f32_16x16x32_bf16 v[86:89], v[150:153], v[174:177], v[86:89]
	v_mfma_f32_16x16x32_bf16 v[82:85], v[158:161], v[174:177], v[82:85]
	v_mfma_f32_16x16x32_bf16 v[78:81], v[150:153], v[182:185], v[78:81]
	v_mfma_f32_16x16x32_bf16 v[74:77], v[158:161], v[182:185], v[74:77]
	v_mfma_f32_16x16x32_bf16 v[70:73], v[150:153], v[190:193], v[70:73]
	v_mfma_f32_16x16x32_bf16 v[66:69], v[158:161], v[190:193], v[66:69]
	s_setprio 0
	s_barrier
; #define PG8_STAGE(bufoff, gbase, voff) do { _Pragma("unroll") for (int _i = 0; _i < 2; ++_i) \
;         __builtin_amdgcn_global_load_lds((const unsigned*)((const char*)(gbase) + (voff)[_i]), (LAS unsigned*)(lds + (bufoff) + ldsw + _i * 8192), 16, 0, 0); } while (0)
; #define PG8_LDA(dst, b, h) do { _Pragma("unroll") for (int m = 0; m < 4; ++m) _Pragma("unroll") for (int k = 0; k < 2; ++k) dst[m][k] = *(const LAS bf16x8*)(lds + PG8_SA(b, h) + aoff + m * 2048 + k * 1024); } while (0)
; #define PG8_MMA(ai, bj, At, Bt) do { __builtin_amdgcn_s_setprio(1); _Pragma("unroll") for (int m = 0; m < 4; ++m) _Pragma("unroll") for (int n = 0; n < 2; ++n) _Pragma("unroll") for (int k = 0; k < 2; ++k) \
;         acc[ai][bj][m][n] = __builtin_amdgcn_mfma_f32_16x16x32_bf16(Bt[n][k], At[m][k], acc[ai][bj][m][n], 0, 0, 0); __builtin_amdgcn_s_setprio(0); } while (0)
; #define PG8_WAIT_V(n) asm volatile("s_waitcnt vmcnt(" #n ")" ::: "memory")
; #define PG8_WAIT_L(n) asm volatile("s_waitcnt lgkmcnt(" #n ")" ::: "memory")
; #define PG8_BAR __builtin_amdgcn_s_barrier()
; #define PG8_SCHED __builtin_amdgcn_sched_barrier(0)
; template <class Epi, class Sched>
; __device__ __forceinline__ void gemm_phase(LAS unsigned char* lds, const Gemm g, const Sched& S, const Epi& E, const int tid) {
;     ...
;             PG8_LDA(At, 1, 1); PG8_STAGE(PG8_SB(1, 0), b3, voffB); PG8_STAGE(PG8_SB(1, 1), b3 + hstepB, voffB); PG8_STAGE(PG8_SA(1, 0), a3, voffA);
;             PG8_WAIT_V(8); PG8_WAIT_L(0); PG8_BAR; PG8_MMA(1, 0, At, B0); PG8_MMA(1, 1, At, B1); PG8_BAR; PG8_SCHED;
;         }
	s_add_i32 s49, s49, s46
	v_lshl_add_u64 v[194:195], v[194:195], 0, s[90:91]
	s_mov_b32 m0, s49
	ds_read_b128 v[162:165], v236 offset:49152
	ds_read_b128 v[166:169], v236 offset:50176
	ds_read_b128 v[170:173], v236 offset:51200
	ds_read_b128 v[174:177], v236 offset:52224
	ds_read_b128 v[178:181], v236 offset:53248
	ds_read_b128 v[182:185], v236 offset:54272
	ds_read_b128 v[186:189], v236 offset:55296
	ds_read_b128 v[190:193], v236 offset:56320
	global_load_lds_dwordx4 v[194:195], off
	s_add_i32 m0, s49, 0x2000
	s_add_u32 s60, s62, 0x40080
	v_lshl_add_u64 v[194:195], v[196:197], 0, s[90:91]
	s_addc_u32 s61, s63, 0
	s_add_i32 s49, s53, s46
	global_load_lds_dwordx4 v[194:195], off
	v_lshl_add_u64 v[194:195], s[60:61], 0, v[206:207]
	s_mov_b32 m0, s49
	s_nop 0
	global_load_lds_dwordx4 v[194:195], off
	v_lshl_add_u64 v[194:195], s[60:61], 0, v[210:211]
	s_add_i32 m0, s49, 0x2000
	s_nop 0
	global_load_lds_dwordx4 v[194:195], off
	v_lshl_add_u64 v[194:195], v[198:199], 0, s[90:91]
	s_mov_b32 m0, s69
	s_nop 0
	global_load_lds_dwordx4 v[194:195], off
	v_lshl_add_u64 v[194:195], v[200:201], 0, s[90:91]
	s_mov_b32 m0, s70
	s_nop 0
	global_load_lds_dwordx4 v[194:195], off
	s_waitcnt vmcnt(8)
	s_waitcnt lgkmcnt(0)
	s_barrier
	s_setprio 1
	s_waitcnt lgkmcnt(0)
	v_mfma_f32_16x16x32_bf16 v[62:65], v[130:133], v[162:165], v[62:65]
	v_mfma_f32_16x16x32_bf16 v[58:61], v[138:141], v[162:165], v[58:61]
	v_mfma_f32_16x16x32_bf16 v[54:57], v[130:133], v[170:173], v[54:57]
	v_mfma_f32_16x16x32_bf16 v[50:53], v[138:141], v[170:173], v[50:53]
	v_mfma_f32_16x16x32_bf16 v[46:49], v[130:133], v[178:181], v[46:49]
	v_mfma_f32_16x16x32_bf16 v[42:45], v[138:141], v[178:181], v[42:45]
	v_mfma_f32_16x16x32_bf16 v[38:41], v[130:133], v[186:189], v[38:41]
	v_mfma_f32_16x16x32_bf16 v[34:37], v[138:141], v[186:189], v[34:37]
	v_mfma_f32_16x16x32_bf16 v[62:65], v[134:137], v[166:169], v[62:65]
	v_mfma_f32_16x16x32_bf16 v[58:61], v[142:145], v[166:169], v[58:61]
	v_mfma_f32_16x16x32_bf16 v[54:57], v[134:137], v[174:177], v[54:57]
	v_mfma_f32_16x16x32_bf16 v[50:53], v[142:145], v[174:177], v[50:53]
	v_mfma_f32_16x16x32_bf16 v[46:49], v[134:137], v[182:185], v[46:49]
	v_mfma_f32_16x16x32_bf16 v[42:45], v[142:145], v[182:185], v[42:45]
	v_mfma_f32_16x16x32_bf16 v[38:41], v[134:137], v[190:193], v[38:41]
	v_mfma_f32_16x16x32_bf16 v[34:37], v[142:145], v[190:193], v[34:37]
	s_setprio 0
	s_setprio 1
	v_mfma_f32_16x16x32_bf16 v[30:33], v[146:149], v[162:165], v[30:33]
	v_mfma_f32_16x16x32_bf16 v[26:29], v[154:157], v[162:165], v[26:29]
	v_mfma_f32_16x16x32_bf16 v[22:25], v[146:149], v[170:173], v[22:25]
	v_mfma_f32_16x16x32_bf16 v[18:21], v[154:157], v[170:173], v[18:21]
	v_mfma_f32_16x16x32_bf16 v[14:17], v[146:149], v[178:181], v[14:17]
	v_mfma_f32_16x16x32_bf16 v[10:13], v[154:157], v[178:181], v[10:13]
	v_mfma_f32_16x16x32_bf16 v[6:9], v[146:149], v[186:189], v[6:9]
	v_mfma_f32_16x16x32_bf16 v[2:5], v[154:157], v[186:189], v[2:5]
	v_mfma_f32_16x16x32_bf16 v[30:33], v[150:153], v[166:169], v[30:33]
	v_mfma_f32_16x16x32_bf16 v[26:29], v[158:161], v[166:169], v[26:29]
	v_mfma_f32_16x16x32_bf16 v[22:25], v[150:153], v[174:177], v[22:25]
	v_mfma_f32_16x16x32_bf16 v[18:21], v[158:161], v[174:177], v[18:21]
	v_mfma_f32_16x16x32_bf16 v[14:17], v[150:153], v[182:185], v[14:17]
	v_mfma_f32_16x16x32_bf16 v[10:13], v[158:161], v[182:185], v[10:13]
	v_mfma_f32_16x16x32_bf16 v[6:9], v[150:153], v[190:193], v[6:9]
	v_mfma_f32_16x16x32_bf16 v[2:5], v[158:161], v[190:193], v[2:5]
	s_setprio 0
	s_barrier
	s_add_i32 s45, s45, 2
	s_add_u32 s43, s43, 0x100
	s_addc_u32 s44, s44, 0
	s_cmp_gt_u32 s45, 13
	s_mov_b64 s[60:61], s[40:41]
	s_cbranch_scc0 .LBB1_156
	s_and_b64 vcc, exec, s[26:27]
	s_cbranch_vccz .LBB1_159
	s_barrier

; #define PG8_STAGE(bufoff, gbase, voff) do { _Pragma("unroll") for (int _i = 0; _i < 2; ++_i) \
;         __builtin_amdgcn_global_load_lds((const unsigned*)((const char*)(gbase) + (voff)[_i]), (LAS unsigned*)(lds + (bufoff) + ldsw + _i * 8192), 16, 0, 0); } while (0)
; #define PG8_LDA(dst, b, h) do { _Pragma("unroll") for (int m = 0; m < 4; ++m) _Pragma("unroll") for (int k = 0; k < 2; ++k) dst[m][k] = *(const LAS bf16x8*)(lds + PG8_SA(b, h) + aoff + m * 2048 + k * 1024); } while (0)
; #define PG8_LDB(dst, b, h) do { _Pragma("unroll") for (int n = 0; n < 2; ++n) _Pragma("unroll") for (int k = 0; k < 2; ++k) dst[n][k] = *(const LAS bf16x8*)(lds + PG8_SB(b, h) + boff + n * 2048 + k * 1024); } while (0)
; #define PG8_MMA(ai, bj, At, Bt) do { __builtin_amdgcn_s_setprio(1); _Pragma("unroll") for (int m = 0; m < 4; ++m) _Pragma("unroll") for (int n = 0; n < 2; ++n) _Pragma("unroll") for (int k = 0; k < 2; ++k) \
;         acc[ai][bj][m][n] = __builtin_amdgcn_mfma_f32_16x16x32_bf16(Bt[n][k], At[m][k], acc[ai][bj][m][n], 0, 0, 0); __builtin_amdgcn_s_setprio(0); } while (0)
; #define PG8_WAIT_V(n) asm volatile("s_waitcnt vmcnt(" #n ")" ::: "memory")
; #define PG8_WAIT_L(n) asm volatile("s_waitcnt lgkmcnt(" #n ")" ::: "memory")
; #define PG8_BAR __builtin_amdgcn_s_barrier()
; #define PG8_SCHED __builtin_amdgcn_sched_barrier(0)
; template <class Epi, class Sched>
; __device__ __forceinline__ void gemm_phase(LAS unsigned char* lds, const Gemm g, const Sched& S, const Epi& E, const int tid) {
;     ...
;         for (int t = 0; t < nt; t += 2) {
;             const bool last = (t == nt - 2);
;             const char* a1 = cA + (size_t)(t + 1) * kstep;
;             const char* a2 = last ? nA : cA + (size_t)(t + 2) * kstep; const char* b2 = last ? nB : cB + (size_t)(t + 2) * kstep;
;             const char* a3 = a2 + kstep; const char* b3 = b2 + kstep;
;             PG8_LDB(B0, 0, 0); PG8_LDB(B1, 0, 1); PG8_SCHED; PG8_LDA(At, 0, 0); PG8_STAGE(PG8_SA(1, 1), a1 + hstepA, voffA);
;             PG8_WAIT_V(8); PG8_WAIT_L(0); PG8_BAR; PG8_MMA(0, 0, At, B0); PG8_MMA(0, 1, At, B1); PG8_BAR; PG8_SCHED;
;             PG8_LDA(At, 0, 1); PG8_STAGE(PG8_SB(0, 0), b2, voffB); PG8_STAGE(PG8_SB(0, 1), b2 + hstepB, voffB); PG8_STAGE(PG8_SA(0, 0), a2, voffA);
;             PG8_WAIT_V(8); PG8_WAIT_L(0); PG8_BAR; PG8_MMA(1, 0, At, B0); PG8_MMA(1, 1, At, B1); PG8_BAR; PG8_SCHED;
.LBB1_574:
	s_add_u32 s14, s44, 0xfff80080
	s_addc_u32 s15, s45, -1
	s_add_i32 s82, 0, 0x10000
	s_cmp_eq_u32 s81, 28
	s_cselect_b32 s73, s43, s15
	s_cselect_b32 s72, s47, s14
	v_add_u32_e32 v148, s82, v151
	s_cselect_b32 s71, s61, s80
	s_cselect_b32 s70, s65, s79
	s_add_i32 s83, 0, 0x14000
	ds_read_b128 v[144:147], v148
	ds_read_b128 v[158:161], v148 offset:1024
	ds_read_b128 v[162:165], v148 offset:2048
	ds_read_b128 v[166:169], v148 offset:3072
	v_add_u32_e32 v148, s83, v151
	ds_read_b128 v[170:173], v148
	ds_read_b128 v[174:177], v148 offset:1024
	ds_read_b128 v[178:181], v148 offset:2048
	ds_read_b128 v[182:185], v148 offset:3072
	v_lshl_add_u64 v[148:149], s[44:45], 0, v[142:143]
	s_add_i32 m0, s57, 0xc000
	ds_read_b128 v[186:189], v156
	ds_read_b128 v[190:193], v156 offset:1024
	ds_read_b128 v[204:207], v156 offset:2048
	ds_read_b128 v[208:211], v156 offset:3072
	ds_read_b128 v[212:215], v156 offset:4096
	ds_read_b128 v[216:219], v156 offset:5120
	ds_read_b128 v[220:223], v156 offset:6144
	ds_read_b128 v[230:233], v156 offset:7168
	global_load_lds_dwordx4 v[148:149], off
	v_lshl_add_u64 v[148:149], s[44:45], 0, v[140:141]
	s_add_i32 m0, s57, 0xe000
	s_nop 0
	global_load_lds_dwordx4 v[148:149], off
	s_waitcnt vmcnt(8)
	s_waitcnt lgkmcnt(0)
	s_barrier
	s_setprio 1
	s_waitcnt lgkmcnt(0)
	v_mfma_f32_16x16x32_bf16 v[126:129], v[144:147], v[186:189], v[126:129]
	v_mfma_f32_16x16x32_bf16 v[122:125], v[162:165], v[186:189], v[122:125]
	v_mfma_f32_16x16x32_bf16 v[110:113], v[144:147], v[204:207], v[110:113]
	v_mfma_f32_16x16x32_bf16 v[106:109], v[162:165], v[204:207], v[106:109]
	v_mfma_f32_16x16x32_bf16 v[94:97], v[144:147], v[212:215], v[94:97]
	v_mfma_f32_16x16x32_bf16 v[90:93], v[162:165], v[212:215], v[90:93]
	v_mfma_f32_16x16x32_bf16 v[78:81], v[144:147], v[220:223], v[78:81]
	v_mfma_f32_16x16x32_bf16 v[74:77], v[162:165], v[220:223], v[74:77]
	v_mfma_f32_16x16x32_bf16 v[126:129], v[158:161], v[190:193], v[126:129]
	v_mfma_f32_16x16x32_bf16 v[122:125], v[166:169], v[190:193], v[122:125]
	v_mfma_f32_16x16x32_bf16 v[110:113], v[158:161], v[208:211], v[110:113]
	v_mfma_f32_16x16x32_bf16 v[106:109], v[166:169], v[208:211], v[106:109]
	v_mfma_f32_16x16x32_bf16 v[94:97], v[158:161], v[216:219], v[94:97]
	v_mfma_f32_16x16x32_bf16 v[90:93], v[166:169], v[216:219], v[90:93]
	v_mfma_f32_16x16x32_bf16 v[78:81], v[158:161], v[230:233], v[78:81]
	v_mfma_f32_16x16x32_bf16 v[74:77], v[166:169], v[230:233], v[74:77]
	s_setprio 0
	s_setprio 1
	v_mfma_f32_16x16x32_bf16 v[118:121], v[170:173], v[186:189], v[118:121]
	v_mfma_f32_16x16x32_bf16 v[114:117], v[178:181], v[186:189], v[114:117]
	v_mfma_f32_16x16x32_bf16 v[102:105], v[170:173], v[204:207], v[102:105]
	v_mfma_f32_16x16x32_bf16 v[98:101], v[178:181], v[204:207], v[98:101]
	v_mfma_f32_16x16x32_bf16 v[86:89], v[170:173], v[212:215], v[86:89]
	v_mfma_f32_16x16x32_bf16 v[82:85], v[178:181], v[212:215], v[82:85]
	v_mfma_f32_16x16x32_bf16 v[70:73], v[170:173], v[220:223], v[70:73]
	v_mfma_f32_16x16x32_bf16 v[66:69], v[178:181], v[220:223], v[66:69]
	v_mfma_f32_16x16x32_bf16 v[118:121], v[174:177], v[190:193], v[118:121]
	v_mfma_f32_16x16x32_bf16 v[114:117], v[182:185], v[190:193], v[114:117]
	v_mfma_f32_16x16x32_bf16 v[102:105], v[174:177], v[208:211], v[102:105]
	v_mfma_f32_16x16x32_bf16 v[98:101], v[182:185], v[208:211], v[98:101]
	v_mfma_f32_16x16x32_bf16 v[86:89], v[174:177], v[216:219], v[86:89]
	v_mfma_f32_16x16x32_bf16 v[82:85], v[182:185], v[216:219], v[82:85]
	v_mfma_f32_16x16x32_bf16 v[70:73], v[174:177], v[230:233], v[70:73]
	v_mfma_f32_16x16x32_bf16 v[66:69], v[182:185], v[230:233], v[66:69]
	s_setprio 0
	s_barrier
	s_add_i32 s14, s82, s56
	v_lshl_add_u64 v[148:149], s[70:71], 0, v[0:1]
	s_mov_b32 m0, s14
	ds_read_b128 v[186:189], v156 offset:16384
	ds_read_b128 v[190:193], v156 offset:17408
	ds_read_b128 v[204:207], v156 offset:18432
	ds_read_b128 v[208:211], v156 offset:19456
	ds_read_b128 v[212:215], v156 offset:20480
	ds_read_b128 v[216:219], v156 offset:21504
	ds_read_b128 v[220:223], v156 offset:22528
	ds_read_b128 v[230:233], v156 offset:23552
	global_load_lds_dwordx4 v[148:149], off
	s_add_i32 m0, s14, 0x2000
	s_add_u32 s14, s70, 0x80000
	v_lshl_add_u64 v[194:195], s[70:71], 0, v[134:135]
	s_addc_u32 s15, s71, 0
	s_add_i32 s82, s83, s56
	global_load_lds_dwordx4 v[194:195], off
	v_lshl_add_u64 v[196:197], s[14:15], 0, v[0:1]
	s_mov_b32 m0, s82
	v_lshl_add_u64 v[198:199], s[72:73], 0, v[132:133]
	global_load_lds_dwordx4 v[196:197], off
	v_lshl_add_u64 v[196:197], s[14:15], 0, v[134:135]
	s_add_i32 m0, s82, 0x2000
	s_nop 0
	global_load_lds_dwordx4 v[196:197], off
	v_lshl_add_u64 v[196:197], s[72:73], 0, v[130:131]
	s_waitcnt vmcnt(6)
	s_waitcnt lgkmcnt(0)
	s_barrier
; #define PG8_STAGE(bufoff, gbase, voff) do { _Pragma("unroll") for (int _i = 0; _i < 2; ++_i) \
;         __builtin_amdgcn_global_load_lds((const unsigned*)((const char*)(gbase) + (voff)[_i]), (LAS unsigned*)(lds + (bufoff) + ldsw + _i * 8192), 16, 0, 0); } while (0)
; #define PG8_LDA(dst, b, h) do { _Pragma("unroll") for (int m = 0; m < 4; ++m) _Pragma("unroll") for (int k = 0; k < 2; ++k) dst[m][k] = *(const LAS bf16x8*)(lds + PG8_SA(b, h) + aoff + m * 2048 + k * 1024); } while (0)
; #define PG8_LDB(dst, b, h) do { _Pragma("unroll") for (int n = 0; n < 2; ++n) _Pragma("unroll") for (int k = 0; k < 2; ++k) dst[n][k] = *(const LAS bf16x8*)(lds + PG8_SB(b, h) + boff + n * 2048 + k * 1024); } while (0)
; #define PG8_MMA(ai, bj, At, Bt) do { __builtin_amdgcn_s_setprio(1); _Pragma("unroll") for (int m = 0; m < 4; ++m) _Pragma("unroll") for (int n = 0; n < 2; ++n) _Pragma("unroll") for (int k = 0; k < 2; ++k) \
;         acc[ai][bj][m][n] = __builtin_amdgcn_mfma_f32_16x16x32_bf16(Bt[n][k], At[m][k], acc[ai][bj][m][n], 0, 0, 0); __builtin_amdgcn_s_setprio(0); } while (0)
; #define PG8_WAIT_V(n) asm volatile("s_waitcnt vmcnt(" #n ")" ::: "memory")
; #define PG8_WAIT_L(n) asm volatile("s_waitcnt lgkmcnt(" #n ")" ::: "memory")
; #define PG8_BAR __builtin_amdgcn_s_barrier()
; #define PG8_SCHED __builtin_amdgcn_sched_barrier(0)
; template <class Epi, class Sched>
; __device__ __forceinline__ void gemm_phase(LAS unsigned char* lds, const Gemm g, const Sched& S, const Epi& E, const int tid) {
;     ...
;             PG8_WAIT_V(8); PG8_WAIT_L(0); PG8_BAR; PG8_MMA(1, 0, At, B0); PG8_MMA(1, 1, At, B1); PG8_BAR; PG8_SCHED;
;             PG8_LDB(B0, 1, 0); PG8_LDB(B1, 1, 1); PG8_SCHED; PG8_LDA(At, 1, 0); PG8_STAGE(PG8_SA(0, 1), a2 + hstepA, voffA);
;             PG8_WAIT_V(8); PG8_WAIT_L(0); PG8_BAR; PG8_MMA(0, 0, At, B0); PG8_MMA(0, 1, At, B1); PG8_BAR; PG8_SCHED;
	s_setprio 1
	s_waitcnt lgkmcnt(0)
	v_mfma_f32_16x16x32_bf16 v[62:65], v[144:147], v[186:189], v[62:65]
	v_mfma_f32_16x16x32_bf16 v[58:61], v[162:165], v[186:189], v[58:61]
	v_mfma_f32_16x16x32_bf16 v[46:49], v[144:147], v[204:207], v[46:49]
	v_mfma_f32_16x16x32_bf16 v[42:45], v[162:165], v[204:207], v[42:45]
	v_mfma_f32_16x16x32_bf16 v[30:33], v[144:147], v[212:215], v[30:33]
	v_mfma_f32_16x16x32_bf16 v[26:29], v[162:165], v[212:215], v[26:29]
	v_mfma_f32_16x16x32_bf16 v[14:17], v[144:147], v[220:223], v[14:17]
	v_mfma_f32_16x16x32_bf16 v[10:13], v[162:165], v[220:223], v[10:13]
	v_mfma_f32_16x16x32_bf16 v[62:65], v[158:161], v[190:193], v[62:65]
	v_mfma_f32_16x16x32_bf16 v[58:61], v[166:169], v[190:193], v[58:61]
	v_mfma_f32_16x16x32_bf16 v[46:49], v[158:161], v[208:211], v[46:49]
	v_mfma_f32_16x16x32_bf16 v[42:45], v[166:169], v[208:211], v[42:45]
	v_mfma_f32_16x16x32_bf16 v[30:33], v[158:161], v[216:219], v[30:33]
	v_mfma_f32_16x16x32_bf16 v[26:29], v[166:169], v[216:219], v[26:29]
	v_mfma_f32_16x16x32_bf16 v[14:17], v[158:161], v[230:233], v[14:17]
	v_mfma_f32_16x16x32_bf16 v[10:13], v[166:169], v[230:233], v[10:13]
	s_setprio 0
	s_setprio 1
	v_mfma_f32_16x16x32_bf16 v[54:57], v[170:173], v[186:189], v[54:57]
	v_mfma_f32_16x16x32_bf16 v[50:53], v[178:181], v[186:189], v[50:53]
	v_mfma_f32_16x16x32_bf16 v[38:41], v[170:173], v[204:207], v[38:41]
	v_mfma_f32_16x16x32_bf16 v[34:37], v[178:181], v[204:207], v[34:37]
	v_mfma_f32_16x16x32_bf16 v[22:25], v[170:173], v[212:215], v[22:25]
	v_mfma_f32_16x16x32_bf16 v[18:21], v[178:181], v[212:215], v[18:21]
	v_mfma_f32_16x16x32_bf16 v[6:9], v[170:173], v[220:223], v[6:9]
	v_mfma_f32_16x16x32_bf16 v[2:5], v[178:181], v[220:223], v[2:5]
	v_mfma_f32_16x16x32_bf16 v[54:57], v[174:177], v[190:193], v[54:57]
	v_mfma_f32_16x16x32_bf16 v[50:53], v[182:185], v[190:193], v[50:53]
	v_mfma_f32_16x16x32_bf16 v[38:41], v[174:177], v[208:211], v[38:41]
	v_mfma_f32_16x16x32_bf16 v[34:37], v[182:185], v[208:211], v[34:37]
	v_mfma_f32_16x16x32_bf16 v[22:25], v[174:177], v[216:219], v[22:25]
	v_mfma_f32_16x16x32_bf16 v[18:21], v[182:185], v[216:219], v[18:21]
	v_mfma_f32_16x16x32_bf16 v[6:9], v[174:177], v[230:233], v[6:9]
	v_mfma_f32_16x16x32_bf16 v[2:5], v[182:185], v[230:233], v[2:5]
	s_setprio 0
	s_barrier
	s_add_i32 s82, 0, 0x18000
	v_add_u32_e32 v157, s82, v151
	s_add_i32 s83, 0, 0x1c000
	ds_read_b128 v[144:147], v157
	ds_read_b128 v[158:161], v157 offset:1024
	ds_read_b128 v[162:165], v157 offset:2048
	ds_read_b128 v[166:169], v157 offset:3072
	v_add_u32_e32 v157, s83, v151
	ds_read_b128 v[170:173], v157
	ds_read_b128 v[174:177], v157 offset:1024
	ds_read_b128 v[178:181], v157 offset:2048
	ds_read_b128 v[182:185], v157 offset:3072
	s_add_u32 s14, s72, 0x80000
	s_addc_u32 s15, s73, 0
	s_mov_b32 m0, s57
	s_nop 0
	global_load_lds_dwordx4 v[196:197], off
	s_mov_b32 m0, s74
	s_nop 0
	global_load_lds_dwordx4 v[198:199], off
	s_mov_b32 m0, s75
	v_lshl_add_u64 v[200:201], s[14:15], 0, v[130:131]
	ds_read_b128 v[186:189], v156 offset:32768
	ds_read_b128 v[190:193], v156 offset:33792
	ds_read_b128 v[204:207], v156 offset:34816
	ds_read_b128 v[208:211], v156 offset:35840
	ds_read_b128 v[212:215], v156 offset:36864
	ds_read_b128 v[216:219], v156 offset:37888
	ds_read_b128 v[220:223], v156 offset:38912
	ds_read_b128 v[230:233], v156 offset:39936
	global_load_lds_dwordx4 v[200:201], off
	v_lshl_add_u64 v[200:201], s[14:15], 0, v[132:133]
	s_mov_b32 m0, s76
	s_nop 0
	global_load_lds_dwordx4 v[200:201], off
	s_waitcnt vmcnt(8)
	s_waitcnt lgkmcnt(0)
	s_barrier
	s_setprio 1
	s_waitcnt lgkmcnt(0)
	v_mfma_f32_16x16x32_bf16 v[126:129], v[144:147], v[186:189], v[126:129]
	v_mfma_f32_16x16x32_bf16 v[122:125], v[162:165], v[186:189], v[122:125]
	v_mfma_f32_16x16x32_bf16 v[110:113], v[144:147], v[204:207], v[110:113]
	v_mfma_f32_16x16x32_bf16 v[106:109], v[162:165], v[204:207], v[106:109]
	v_mfma_f32_16x16x32_bf16 v[94:97], v[144:147], v[212:215], v[94:97]
	v_mfma_f32_16x16x32_bf16 v[90:93], v[162:165], v[212:215], v[90:93]
	v_mfma_f32_16x16x32_bf16 v[78:81], v[144:147], v[220:223], v[78:81]
	v_mfma_f32_16x16x32_bf16 v[74:77], v[162:165], v[220:223], v[74:77]
	v_mfma_f32_16x16x32_bf16 v[126:129], v[158:161], v[190:193], v[126:129]
	v_mfma_f32_16x16x32_bf16 v[122:125], v[166:169], v[190:193], v[122:125]
	v_mfma_f32_16x16x32_bf16 v[110:113], v[158:161], v[208:211], v[110:113]
	v_mfma_f32_16x16x32_bf16 v[106:109], v[166:169], v[208:211], v[106:109]
	v_mfma_f32_16x16x32_bf16 v[94:97], v[158:161], v[216:219], v[94:97]
	v_mfma_f32_16x16x32_bf16 v[90:93], v[166:169], v[216:219], v[90:93]
	v_mfma_f32_16x16x32_bf16 v[78:81], v[158:161], v[230:233], v[78:81]
	v_mfma_f32_16x16x32_bf16 v[74:77], v[166:169], v[230:233], v[74:77]
	s_setprio 0
	s_setprio 1
	v_mfma_f32_16x16x32_bf16 v[118:121], v[170:173], v[186:189], v[118:121]
	v_mfma_f32_16x16x32_bf16 v[114:117], v[178:181], v[186:189], v[114:117]
	v_mfma_f32_16x16x32_bf16 v[102:105], v[170:173], v[204:207], v[102:105]
	v_mfma_f32_16x16x32_bf16 v[98:101], v[178:181], v[204:207], v[98:101]
	v_mfma_f32_16x16x32_bf16 v[86:89], v[170:173], v[212:215], v[86:89]
	v_mfma_f32_16x16x32_bf16 v[82:85], v[178:181], v[212:215], v[82:85]
	v_mfma_f32_16x16x32_bf16 v[70:73], v[170:173], v[220:223], v[70:73]
	v_mfma_f32_16x16x32_bf16 v[66:69], v[178:181], v[220:223], v[66:69]
	v_mfma_f32_16x16x32_bf16 v[118:121], v[174:177], v[190:193], v[118:121]
	v_mfma_f32_16x16x32_bf16 v[114:117], v[182:185], v[190:193], v[114:117]
	v_mfma_f32_16x16x32_bf16 v[102:105], v[174:177], v[208:211], v[102:105]
	v_mfma_f32_16x16x32_bf16 v[98:101], v[182:185], v[208:211], v[98:101]
	v_mfma_f32_16x16x32_bf16 v[86:89], v[174:177], v[216:219], v[86:89]
	v_mfma_f32_16x16x32_bf16 v[82:85], v[182:185], v[216:219], v[82:85]
	v_mfma_f32_16x16x32_bf16 v[70:73], v[174:177], v[230:233], v[70:73]
	v_mfma_f32_16x16x32_bf16 v[66:69], v[182:185], v[230:233], v[66:69]
	s_setprio 0
	s_barrier
; #define PG8_STAGE(bufoff, gbase, voff) do { _Pragma("unroll") for (int _i = 0; _i < 2; ++_i) \
;         __builtin_amdgcn_global_load_lds((const unsigned*)((const char*)(gbase) + (voff)[_i]), (LAS unsigned*)(lds + (bufoff) + ldsw + _i * 8192), 16, 0, 0); } while (0)
; #define PG8_LDA(dst, b, h) do { _Pragma("unroll") for (int m = 0; m < 4; ++m) _Pragma("unroll") for (int k = 0; k < 2; ++k) dst[m][k] = *(const LAS bf16x8*)(lds + PG8_SA(b, h) + aoff + m * 2048 + k * 1024); } while (0)
; #define PG8_MMA(ai, bj, At, Bt) do { __builtin_amdgcn_s_setprio(1); _Pragma("unroll") for (int m = 0; m < 4; ++m) _Pragma("unroll") for (int n = 0; n < 2; ++n) _Pragma("unroll") for (int k = 0; k < 2; ++k) \
;         acc[ai][bj][m][n] = __builtin_amdgcn_mfma_f32_16x16x32_bf16(Bt[n][k], At[m][k], acc[ai][bj][m][n], 0, 0, 0); __builtin_amdgcn_s_setprio(0); } while (0)
; #define PG8_WAIT_V(n) asm volatile("s_waitcnt vmcnt(" #n ")" ::: "memory")
; #define PG8_WAIT_L(n) asm volatile("s_waitcnt lgkmcnt(" #n ")" ::: "memory")
; #define PG8_BAR __builtin_amdgcn_s_barrier()
; #define PG8_SCHED __builtin_amdgcn_sched_barrier(0)
; template <class Epi, class Sched>
; __device__ __forceinline__ void gemm_phase(LAS unsigned char* lds, const Gemm g, const Sched& S, const Epi& E, const int tid) {
;     ...
;             PG8_LDA(At, 1, 1); PG8_STAGE(PG8_SB(1, 0), b3, voffB); PG8_STAGE(PG8_SB(1, 1), b3 + hstepB, voffB); PG8_STAGE(PG8_SA(1, 0), a3, voffA);
;             PG8_WAIT_V(8); PG8_WAIT_L(0); PG8_BAR; PG8_MMA(1, 0, At, B0); PG8_MMA(1, 1, At, B1); PG8_BAR; PG8_SCHED;
;         }
	s_add_i32 s14, s82, s56
	v_lshl_add_u64 v[148:149], v[148:149], 0, s[90:91]
	s_mov_b32 m0, s14
	ds_read_b128 v[186:189], v156 offset:49152
	ds_read_b128 v[190:193], v156 offset:50176
	ds_read_b128 v[204:207], v156 offset:51200
	ds_read_b128 v[208:211], v156 offset:52224
	ds_read_b128 v[212:215], v156 offset:53248
	ds_read_b128 v[216:219], v156 offset:54272
	ds_read_b128 v[220:223], v156 offset:55296
	ds_read_b128 v[230:233], v156 offset:56320
	global_load_lds_dwordx4 v[148:149], off
	s_add_i32 m0, s14, 0x2000
	s_add_u32 s14, s70, 0x80080
	v_lshl_add_u64 v[148:149], v[194:195], 0, s[90:91]
	s_addc_u32 s15, s71, 0
	s_add_i32 s70, s83, s56
	global_load_lds_dwordx4 v[148:149], off
	v_lshl_add_u64 v[148:149], s[14:15], 0, v[0:1]
	s_mov_b32 m0, s70
	s_nop 0
	global_load_lds_dwordx4 v[148:149], off
	v_lshl_add_u64 v[148:149], s[14:15], 0, v[134:135]
	s_add_i32 m0, s70, 0x2000
	s_nop 0
	global_load_lds_dwordx4 v[148:149], off
	v_lshl_add_u64 v[148:149], v[196:197], 0, s[90:91]
	s_mov_b32 m0, s77
	s_nop 0
	global_load_lds_dwordx4 v[148:149], off
	v_lshl_add_u64 v[148:149], v[198:199], 0, s[90:91]
	s_mov_b32 m0, s78
	s_nop 0
	global_load_lds_dwordx4 v[148:149], off
	s_waitcnt vmcnt(8)
	s_waitcnt lgkmcnt(0)
	s_barrier
	s_setprio 1
	s_waitcnt lgkmcnt(0)
	v_mfma_f32_16x16x32_bf16 v[62:65], v[144:147], v[186:189], v[62:65]
	v_mfma_f32_16x16x32_bf16 v[58:61], v[162:165], v[186:189], v[58:61]
	v_mfma_f32_16x16x32_bf16 v[46:49], v[144:147], v[204:207], v[46:49]
	v_mfma_f32_16x16x32_bf16 v[42:45], v[162:165], v[204:207], v[42:45]
	v_mfma_f32_16x16x32_bf16 v[30:33], v[144:147], v[212:215], v[30:33]
	v_mfma_f32_16x16x32_bf16 v[26:29], v[162:165], v[212:215], v[26:29]
	v_mfma_f32_16x16x32_bf16 v[14:17], v[144:147], v[220:223], v[14:17]
	v_mfma_f32_16x16x32_bf16 v[10:13], v[162:165], v[220:223], v[10:13]
	v_mfma_f32_16x16x32_bf16 v[62:65], v[158:161], v[190:193], v[62:65]
	v_mfma_f32_16x16x32_bf16 v[58:61], v[166:169], v[190:193], v[58:61]
	v_mfma_f32_16x16x32_bf16 v[46:49], v[158:161], v[208:211], v[46:49]
	v_mfma_f32_16x16x32_bf16 v[42:45], v[166:169], v[208:211], v[42:45]
	v_mfma_f32_16x16x32_bf16 v[30:33], v[158:161], v[216:219], v[30:33]
	v_mfma_f32_16x16x32_bf16 v[26:29], v[166:169], v[216:219], v[26:29]
	v_mfma_f32_16x16x32_bf16 v[14:17], v[158:161], v[230:233], v[14:17]
	v_mfma_f32_16x16x32_bf16 v[10:13], v[166:169], v[230:233], v[10:13]
	s_setprio 0
	s_setprio 1
	v_mfma_f32_16x16x32_bf16 v[54:57], v[170:173], v[186:189], v[54:57]
	v_mfma_f32_16x16x32_bf16 v[50:53], v[178:181], v[186:189], v[50:53]
	v_mfma_f32_16x16x32_bf16 v[38:41], v[170:173], v[204:207], v[38:41]
	v_mfma_f32_16x16x32_bf16 v[34:37], v[178:181], v[204:207], v[34:37]
	v_mfma_f32_16x16x32_bf16 v[22:25], v[170:173], v[212:215], v[22:25]
	v_mfma_f32_16x16x32_bf16 v[18:21], v[178:181], v[212:215], v[18:21]
	v_mfma_f32_16x16x32_bf16 v[6:9], v[170:173], v[220:223], v[6:9]
	v_mfma_f32_16x16x32_bf16 v[2:5], v[178:181], v[220:223], v[2:5]
	v_mfma_f32_16x16x32_bf16 v[54:57], v[174:177], v[190:193], v[54:57]
	v_mfma_f32_16x16x32_bf16 v[50:53], v[182:185], v[190:193], v[50:53]
	v_mfma_f32_16x16x32_bf16 v[38:41], v[174:177], v[208:211], v[38:41]
	v_mfma_f32_16x16x32_bf16 v[34:37], v[182:185], v[208:211], v[34:37]
	v_mfma_f32_16x16x32_bf16 v[22:25], v[174:177], v[216:219], v[22:25]
	v_mfma_f32_16x16x32_bf16 v[18:21], v[182:185], v[216:219], v[18:21]
	v_mfma_f32_16x16x32_bf16 v[6:9], v[174:177], v[230:233], v[6:9]
	v_mfma_f32_16x16x32_bf16 v[2:5], v[182:185], v[230:233], v[2:5]
	s_setprio 0
	s_barrier
	s_add_i32 s81, s81, 2
	s_add_u32 s79, s79, 0x100
	s_addc_u32 s80, s80, 0
	s_add_u32 s44, s44, 0x100
	s_addc_u32 s45, s45, 0
	s_cmp_gt_u32 s81, 29
	s_cbranch_scc0 .LBB1_574
	s_and_b64 vcc, exec, s[36:37]
	s_cbranch_vccz .LBB1_577
	s_barrier

; #define PG8_STAGE(bufoff, gbase, voff) do { _Pragma("unroll") for (int _i = 0; _i < 2; ++_i) \
;         __builtin_amdgcn_global_load_lds((const unsigned*)((const char*)(gbase) + (voff)[_i]), (LAS unsigned*)(lds + (bufoff) + ldsw + _i * 8192), 16, 0, 0); } while (0)
; #define PG8_LDA(dst, b, h) do { _Pragma("unroll") for (int m = 0; m < 4; ++m) _Pragma("unroll") for (int k = 0; k < 2; ++k) dst[m][k] = *(const LAS bf16x8*)(lds + PG8_SA(b, h) + aoff + m * 2048 + k * 1024); } while (0)
; #define PG8_LDB(dst, b, h) do { _Pragma("unroll") for (int n = 0; n < 2; ++n) _Pragma("unroll") for (int k = 0; k < 2; ++k) dst[n][k] = *(const LAS bf16x8*)(lds + PG8_SB(b, h) + boff + n * 2048 + k * 1024); } while (0)
; #define PG8_MMA(ai, bj, At, Bt) do { __builtin_amdgcn_s_setprio(1); _Pragma("unroll") for (int m = 0; m < 4; ++m) _Pragma("unroll") for (int n = 0; n < 2; ++n) _Pragma("unroll") for (int k = 0; k < 2; ++k) \
;         acc[ai][bj][m][n] = __builtin_amdgcn_mfma_f32_16x16x32_bf16(Bt[n][k], At[m][k], acc[ai][bj][m][n], 0, 0, 0); __builtin_amdgcn_s_setprio(0); } while (0)
; #define PG8_WAIT_V(n) asm volatile("s_waitcnt vmcnt(" #n ")" ::: "memory")
; #define PG8_WAIT_L(n) asm volatile("s_waitcnt lgkmcnt(" #n ")" ::: "memory")
; #define PG8_BAR __builtin_amdgcn_s_barrier()
; #define PG8_SCHED __builtin_amdgcn_sched_barrier(0)
; template <class Epi, class Sched>
; __device__ __forceinline__ void gemm_phase(LAS unsigned char* lds, const Gemm g, const Sched& S, const Epi& E, const int tid) {
;     ...
;         for (int t = 0; t < nt; t += 2) {
;             const bool last = (t == nt - 2);
;             const char* a1 = cA + (size_t)(t + 1) * kstep;
;             const char* a2 = last ? nA : cA + (size_t)(t + 2) * kstep; const char* b2 = last ? nB : cB + (size_t)(t + 2) * kstep;
;             const char* a3 = a2 + kstep; const char* b3 = b2 + kstep;
;             PG8_LDB(B0, 0, 0); PG8_LDB(B1, 0, 1); PG8_SCHED; PG8_LDA(At, 0, 0); PG8_STAGE(PG8_SA(1, 1), a1 + hstepA, voffA);
;             PG8_WAIT_V(8); PG8_WAIT_L(0); PG8_BAR; PG8_MMA(0, 0, At, B0); PG8_MMA(0, 1, At, B1); PG8_BAR; PG8_SCHED;
;             PG8_LDA(At, 0, 1); PG8_STAGE(PG8_SB(0, 0), b2, voffB); PG8_STAGE(PG8_SB(0, 1), b2 + hstepB, voffB); PG8_STAGE(PG8_SA(0, 0), a2, voffA);
;             PG8_WAIT_V(8); PG8_WAIT_L(0); PG8_BAR; PG8_MMA(1, 0, At, B0); PG8_MMA(1, 1, At, B1); PG8_BAR; PG8_SCHED;
.LBB1_724:
	s_add_u32 s14, s48, 0xfff80080
	s_addc_u32 s15, s49, -1
	s_add_i32 s72, 0, 0x10000
	s_cmp_eq_u32 s71, 28
	s_cselect_b32 s57, s37, s15
	s_cselect_b32 s56, s41, s14
	v_add_u32_e32 v144, s72, v147
	s_cselect_b32 s53, s27, s70
	s_cselect_b32 s52, s68, s69
	s_add_i32 s73, 0, 0x14000
	ds_read_b128 v[140:143], v144
	ds_read_b128 v[158:161], v144 offset:1024
	ds_read_b128 v[162:165], v144 offset:2048
	ds_read_b128 v[166:169], v144 offset:3072
	v_add_u32_e32 v144, s73, v147
	ds_read_b128 v[170:173], v144
	ds_read_b128 v[174:177], v144 offset:1024
	ds_read_b128 v[178:181], v144 offset:2048
	ds_read_b128 v[182:185], v144 offset:3072
	v_lshl_add_u64 v[144:145], s[48:49], 0, v[138:139]
	s_add_i32 m0, s47, 0xc000
	ds_read_b128 v[186:189], v156
	ds_read_b128 v[190:193], v156 offset:1024
	ds_read_b128 v[204:207], v156 offset:2048
	ds_read_b128 v[208:211], v156 offset:3072
	ds_read_b128 v[212:215], v156 offset:4096
	ds_read_b128 v[216:219], v156 offset:5120
	ds_read_b128 v[220:223], v156 offset:6144
	ds_read_b128 v[230:233], v156 offset:7168
	global_load_lds_dwordx4 v[144:145], off
	v_lshl_add_u64 v[144:145], s[48:49], 0, v[136:137]
	s_add_i32 m0, s47, 0xe000
	s_nop 0
	global_load_lds_dwordx4 v[144:145], off
	s_waitcnt vmcnt(8)
	s_waitcnt lgkmcnt(0)
	s_barrier
	s_setprio 1
	s_waitcnt lgkmcnt(0)
	v_mfma_f32_16x16x32_bf16 v[126:129], v[140:143], v[186:189], v[126:129]
	v_mfma_f32_16x16x32_bf16 v[122:125], v[162:165], v[186:189], v[122:125]
	v_mfma_f32_16x16x32_bf16 v[110:113], v[140:143], v[204:207], v[110:113]
	v_mfma_f32_16x16x32_bf16 v[106:109], v[162:165], v[204:207], v[106:109]
	v_mfma_f32_16x16x32_bf16 v[94:97], v[140:143], v[212:215], v[94:97]
	v_mfma_f32_16x16x32_bf16 v[90:93], v[162:165], v[212:215], v[90:93]
	v_mfma_f32_16x16x32_bf16 v[78:81], v[140:143], v[220:223], v[78:81]
	v_mfma_f32_16x16x32_bf16 v[74:77], v[162:165], v[220:223], v[74:77]
	v_mfma_f32_16x16x32_bf16 v[126:129], v[158:161], v[190:193], v[126:129]
	v_mfma_f32_16x16x32_bf16 v[122:125], v[166:169], v[190:193], v[122:125]
	v_mfma_f32_16x16x32_bf16 v[110:113], v[158:161], v[208:211], v[110:113]
	v_mfma_f32_16x16x32_bf16 v[106:109], v[166:169], v[208:211], v[106:109]
	v_mfma_f32_16x16x32_bf16 v[94:97], v[158:161], v[216:219], v[94:97]
	v_mfma_f32_16x16x32_bf16 v[90:93], v[166:169], v[216:219], v[90:93]
	v_mfma_f32_16x16x32_bf16 v[78:81], v[158:161], v[230:233], v[78:81]
	v_mfma_f32_16x16x32_bf16 v[74:77], v[166:169], v[230:233], v[74:77]
	s_setprio 0
	s_setprio 1
	v_mfma_f32_16x16x32_bf16 v[118:121], v[170:173], v[186:189], v[118:121]
	v_mfma_f32_16x16x32_bf16 v[114:117], v[178:181], v[186:189], v[114:117]
	v_mfma_f32_16x16x32_bf16 v[102:105], v[170:173], v[204:207], v[102:105]
	v_mfma_f32_16x16x32_bf16 v[98:101], v[178:181], v[204:207], v[98:101]
	v_mfma_f32_16x16x32_bf16 v[86:89], v[170:173], v[212:215], v[86:89]
	v_mfma_f32_16x16x32_bf16 v[82:85], v[178:181], v[212:215], v[82:85]
	v_mfma_f32_16x16x32_bf16 v[70:73], v[170:173], v[220:223], v[70:73]
	v_mfma_f32_16x16x32_bf16 v[66:69], v[178:181], v[220:223], v[66:69]
	v_mfma_f32_16x16x32_bf16 v[118:121], v[174:177], v[190:193], v[118:121]
	v_mfma_f32_16x16x32_bf16 v[114:117], v[182:185], v[190:193], v[114:117]
	v_mfma_f32_16x16x32_bf16 v[102:105], v[174:177], v[208:211], v[102:105]
	v_mfma_f32_16x16x32_bf16 v[98:101], v[182:185], v[208:211], v[98:101]
	v_mfma_f32_16x16x32_bf16 v[86:89], v[174:177], v[216:219], v[86:89]
	v_mfma_f32_16x16x32_bf16 v[82:85], v[182:185], v[216:219], v[82:85]
	v_mfma_f32_16x16x32_bf16 v[70:73], v[174:177], v[230:233], v[70:73]
	v_mfma_f32_16x16x32_bf16 v[66:69], v[182:185], v[230:233], v[66:69]
	s_setprio 0
	s_barrier
	s_add_i32 s14, s72, s62
	v_lshl_add_u64 v[144:145], s[52:53], 0, v[0:1]
	s_mov_b32 m0, s14
	ds_read_b128 v[186:189], v156 offset:16384
	ds_read_b128 v[190:193], v156 offset:17408
	ds_read_b128 v[204:207], v156 offset:18432
	ds_read_b128 v[208:211], v156 offset:19456
	ds_read_b128 v[212:215], v156 offset:20480
	ds_read_b128 v[216:219], v156 offset:21504
	ds_read_b128 v[220:223], v156 offset:22528
	ds_read_b128 v[230:233], v156 offset:23552
	global_load_lds_dwordx4 v[144:145], off
	s_add_i32 m0, s14, 0x2000
	s_add_u32 s14, s52, 0x80000
	v_lshl_add_u64 v[194:195], s[52:53], 0, v[134:135]
	s_addc_u32 s15, s53, 0
	s_add_i32 s72, s73, s62
	global_load_lds_dwordx4 v[194:195], off
	v_lshl_add_u64 v[196:197], s[14:15], 0, v[0:1]
	s_mov_b32 m0, s72
	v_lshl_add_u64 v[198:199], s[56:57], 0, v[132:133]
	global_load_lds_dwordx4 v[196:197], off
	v_lshl_add_u64 v[196:197], s[14:15], 0, v[134:135]
	s_add_i32 m0, s72, 0x2000
	s_nop 0
	global_load_lds_dwordx4 v[196:197], off
	v_lshl_add_u64 v[196:197], s[56:57], 0, v[130:131]
	s_waitcnt vmcnt(6)
	s_waitcnt lgkmcnt(0)
	s_barrier
; #define PG8_STAGE(bufoff, gbase, voff) do { _Pragma("unroll") for (int _i = 0; _i < 2; ++_i) \
;         __builtin_amdgcn_global_load_lds((const unsigned*)((const char*)(gbase) + (voff)[_i]), (LAS unsigned*)(lds + (bufoff) + ldsw + _i * 8192), 16, 0, 0); } while (0)
; #define PG8_LDA(dst, b, h) do { _Pragma("unroll") for (int m = 0; m < 4; ++m) _Pragma("unroll") for (int k = 0; k < 2; ++k) dst[m][k] = *(const LAS bf16x8*)(lds + PG8_SA(b, h) + aoff + m * 2048 + k * 1024); } while (0)
; #define PG8_LDB(dst, b, h) do { _Pragma("unroll") for (int n = 0; n < 2; ++n) _Pragma("unroll") for (int k = 0; k < 2; ++k) dst[n][k] = *(const LAS bf16x8*)(lds + PG8_SB(b, h) + boff + n * 2048 + k * 1024); } while (0)
; #define PG8_MMA(ai, bj, At, Bt) do { __builtin_amdgcn_s_setprio(1); _Pragma("unroll") for (int m = 0; m < 4; ++m) _Pragma("unroll") for (int n = 0; n < 2; ++n) _Pragma("unroll") for (int k = 0; k < 2; ++k) \
;         acc[ai][bj][m][n] = __builtin_amdgcn_mfma_f32_16x16x32_bf16(Bt[n][k], At[m][k], acc[ai][bj][m][n], 0, 0, 0); __builtin_amdgcn_s_setprio(0); } while (0)
; #define PG8_WAIT_V(n) asm volatile("s_waitcnt vmcnt(" #n ")" ::: "memory")
; #define PG8_WAIT_L(n) asm volatile("s_waitcnt lgkmcnt(" #n ")" ::: "memory")
; #define PG8_BAR __builtin_amdgcn_s_barrier()
; #define PG8_SCHED __builtin_amdgcn_sched_barrier(0)
; template <class Epi, class Sched>
; __device__ __forceinline__ void gemm_phase(LAS unsigned char* lds, const Gemm g, const Sched& S, const Epi& E, const int tid) {
;     ...
;             PG8_WAIT_V(8); PG8_WAIT_L(0); PG8_BAR; PG8_MMA(1, 0, At, B0); PG8_MMA(1, 1, At, B1); PG8_BAR; PG8_SCHED;
;             PG8_LDB(B0, 1, 0); PG8_LDB(B1, 1, 1); PG8_SCHED; PG8_LDA(At, 1, 0); PG8_STAGE(PG8_SA(0, 1), a2 + hstepA, voffA);
;             PG8_WAIT_V(8); PG8_WAIT_L(0); PG8_BAR; PG8_MMA(0, 0, At, B0); PG8_MMA(0, 1, At, B1); PG8_BAR; PG8_SCHED;
	s_setprio 1
	s_waitcnt lgkmcnt(0)
	v_mfma_f32_16x16x32_bf16 v[62:65], v[140:143], v[186:189], v[62:65]
	v_mfma_f32_16x16x32_bf16 v[58:61], v[162:165], v[186:189], v[58:61]
	v_mfma_f32_16x16x32_bf16 v[46:49], v[140:143], v[204:207], v[46:49]
	v_mfma_f32_16x16x32_bf16 v[42:45], v[162:165], v[204:207], v[42:45]
	v_mfma_f32_16x16x32_bf16 v[30:33], v[140:143], v[212:215], v[30:33]
	v_mfma_f32_16x16x32_bf16 v[26:29], v[162:165], v[212:215], v[26:29]
	v_mfma_f32_16x16x32_bf16 v[14:17], v[140:143], v[220:223], v[14:17]
	v_mfma_f32_16x16x32_bf16 v[10:13], v[162:165], v[220:223], v[10:13]
	v_mfma_f32_16x16x32_bf16 v[62:65], v[158:161], v[190:193], v[62:65]
	v_mfma_f32_16x16x32_bf16 v[58:61], v[166:169], v[190:193], v[58:61]
	v_mfma_f32_16x16x32_bf16 v[46:49], v[158:161], v[208:211], v[46:49]
	v_mfma_f32_16x16x32_bf16 v[42:45], v[166:169], v[208:211], v[42:45]
	v_mfma_f32_16x16x32_bf16 v[30:33], v[158:161], v[216:219], v[30:33]
	v_mfma_f32_16x16x32_bf16 v[26:29], v[166:169], v[216:219], v[26:29]
	v_mfma_f32_16x16x32_bf16 v[14:17], v[158:161], v[230:233], v[14:17]
	v_mfma_f32_16x16x32_bf16 v[10:13], v[166:169], v[230:233], v[10:13]
	s_setprio 0
	s_setprio 1
	v_mfma_f32_16x16x32_bf16 v[54:57], v[170:173], v[186:189], v[54:57]
	v_mfma_f32_16x16x32_bf16 v[50:53], v[178:181], v[186:189], v[50:53]
	v_mfma_f32_16x16x32_bf16 v[38:41], v[170:173], v[204:207], v[38:41]
	v_mfma_f32_16x16x32_bf16 v[34:37], v[178:181], v[204:207], v[34:37]
	v_mfma_f32_16x16x32_bf16 v[22:25], v[170:173], v[212:215], v[22:25]
	v_mfma_f32_16x16x32_bf16 v[18:21], v[178:181], v[212:215], v[18:21]
	v_mfma_f32_16x16x32_bf16 v[6:9], v[170:173], v[220:223], v[6:9]
	v_mfma_f32_16x16x32_bf16 v[2:5], v[178:181], v[220:223], v[2:5]
	v_mfma_f32_16x16x32_bf16 v[54:57], v[174:177], v[190:193], v[54:57]
	v_mfma_f32_16x16x32_bf16 v[50:53], v[182:185], v[190:193], v[50:53]
	v_mfma_f32_16x16x32_bf16 v[38:41], v[174:177], v[208:211], v[38:41]
	v_mfma_f32_16x16x32_bf16 v[34:37], v[182:185], v[208:211], v[34:37]
	v_mfma_f32_16x16x32_bf16 v[22:25], v[174:177], v[216:219], v[22:25]
	v_mfma_f32_16x16x32_bf16 v[18:21], v[182:185], v[216:219], v[18:21]
	v_mfma_f32_16x16x32_bf16 v[6:9], v[174:177], v[230:233], v[6:9]
	v_mfma_f32_16x16x32_bf16 v[2:5], v[182:185], v[230:233], v[2:5]
	s_setprio 0
	s_barrier
	s_add_i32 s72, 0, 0x18000
	v_add_u32_e32 v157, s72, v147
	s_add_i32 s73, 0, 0x1c000
	ds_read_b128 v[140:143], v157
	ds_read_b128 v[158:161], v157 offset:1024
	ds_read_b128 v[162:165], v157 offset:2048
	ds_read_b128 v[166:169], v157 offset:3072
	v_add_u32_e32 v157, s73, v147
	ds_read_b128 v[170:173], v157
	ds_read_b128 v[174:177], v157 offset:1024
	ds_read_b128 v[178:181], v157 offset:2048
	ds_read_b128 v[182:185], v157 offset:3072
	s_add_u32 s14, s56, 0x80000
	s_addc_u32 s15, s57, 0
	s_mov_b32 m0, s47
	s_nop 0
	global_load_lds_dwordx4 v[196:197], off
	s_mov_b32 m0, s63
	s_nop 0
	global_load_lds_dwordx4 v[198:199], off
	s_mov_b32 m0, s64
	v_lshl_add_u64 v[200:201], s[14:15], 0, v[130:131]
	ds_read_b128 v[186:189], v156 offset:32768
	ds_read_b128 v[190:193], v156 offset:33792
	ds_read_b128 v[204:207], v156 offset:34816
	ds_read_b128 v[208:211], v156 offset:35840
	ds_read_b128 v[212:215], v156 offset:36864
	ds_read_b128 v[216:219], v156 offset:37888
	ds_read_b128 v[220:223], v156 offset:38912
	ds_read_b128 v[230:233], v156 offset:39936
	global_load_lds_dwordx4 v[200:201], off
	v_lshl_add_u64 v[200:201], s[14:15], 0, v[132:133]
	s_mov_b32 m0, s65
	s_nop 0
	global_load_lds_dwordx4 v[200:201], off
	s_waitcnt vmcnt(8)
	s_waitcnt lgkmcnt(0)
	s_barrier
	s_setprio 1
	s_waitcnt lgkmcnt(0)
	v_mfma_f32_16x16x32_bf16 v[126:129], v[140:143], v[186:189], v[126:129]
	v_mfma_f32_16x16x32_bf16 v[122:125], v[162:165], v[186:189], v[122:125]
	v_mfma_f32_16x16x32_bf16 v[110:113], v[140:143], v[204:207], v[110:113]
	v_mfma_f32_16x16x32_bf16 v[106:109], v[162:165], v[204:207], v[106:109]
	v_mfma_f32_16x16x32_bf16 v[94:97], v[140:143], v[212:215], v[94:97]
	v_mfma_f32_16x16x32_bf16 v[90:93], v[162:165], v[212:215], v[90:93]
	v_mfma_f32_16x16x32_bf16 v[78:81], v[140:143], v[220:223], v[78:81]
	v_mfma_f32_16x16x32_bf16 v[74:77], v[162:165], v[220:223], v[74:77]
	v_mfma_f32_16x16x32_bf16 v[126:129], v[158:161], v[190:193], v[126:129]
	v_mfma_f32_16x16x32_bf16 v[122:125], v[166:169], v[190:193], v[122:125]
	v_mfma_f32_16x16x32_bf16 v[110:113], v[158:161], v[208:211], v[110:113]
	v_mfma_f32_16x16x32_bf16 v[106:109], v[166:169], v[208:211], v[106:109]
	v_mfma_f32_16x16x32_bf16 v[94:97], v[158:161], v[216:219], v[94:97]
	v_mfma_f32_16x16x32_bf16 v[90:93], v[166:169], v[216:219], v[90:93]
	v_mfma_f32_16x16x32_bf16 v[78:81], v[158:161], v[230:233], v[78:81]
	v_mfma_f32_16x16x32_bf16 v[74:77], v[166:169], v[230:233], v[74:77]
	s_setprio 0
	s_setprio 1
	v_mfma_f32_16x16x32_bf16 v[118:121], v[170:173], v[186:189], v[118:121]
	v_mfma_f32_16x16x32_bf16 v[114:117], v[178:181], v[186:189], v[114:117]
	v_mfma_f32_16x16x32_bf16 v[102:105], v[170:173], v[204:207], v[102:105]
	v_mfma_f32_16x16x32_bf16 v[98:101], v[178:181], v[204:207], v[98:101]
	v_mfma_f32_16x16x32_bf16 v[86:89], v[170:173], v[212:215], v[86:89]
	v_mfma_f32_16x16x32_bf16 v[82:85], v[178:181], v[212:215], v[82:85]
	v_mfma_f32_16x16x32_bf16 v[70:73], v[170:173], v[220:223], v[70:73]
	v_mfma_f32_16x16x32_bf16 v[66:69], v[178:181], v[220:223], v[66:69]
	v_mfma_f32_16x16x32_bf16 v[118:121], v[174:177], v[190:193], v[118:121]
	v_mfma_f32_16x16x32_bf16 v[114:117], v[182:185], v[190:193], v[114:117]
	v_mfma_f32_16x16x32_bf16 v[102:105], v[174:177], v[208:211], v[102:105]
	v_mfma_f32_16x16x32_bf16 v[98:101], v[182:185], v[208:211], v[98:101]
	v_mfma_f32_16x16x32_bf16 v[86:89], v[174:177], v[216:219], v[86:89]
	v_mfma_f32_16x16x32_bf16 v[82:85], v[182:185], v[216:219], v[82:85]
	v_mfma_f32_16x16x32_bf16 v[70:73], v[174:177], v[230:233], v[70:73]
	v_mfma_f32_16x16x32_bf16 v[66:69], v[182:185], v[230:233], v[66:69]
	s_setprio 0
	s_barrier
; #define PG8_STAGE(bufoff, gbase, voff) do { _Pragma("unroll") for (int _i = 0; _i < 2; ++_i) \
;         __builtin_amdgcn_global_load_lds((const unsigned*)((const char*)(gbase) + (voff)[_i]), (LAS unsigned*)(lds + (bufoff) + ldsw + _i * 8192), 16, 0, 0); } while (0)
; #define PG8_LDA(dst, b, h) do { _Pragma("unroll") for (int m = 0; m < 4; ++m) _Pragma("unroll") for (int k = 0; k < 2; ++k) dst[m][k] = *(const LAS bf16x8*)(lds + PG8_SA(b, h) + aoff + m * 2048 + k * 1024); } while (0)
; #define PG8_MMA(ai, bj, At, Bt) do { __builtin_amdgcn_s_setprio(1); _Pragma("unroll") for (int m = 0; m < 4; ++m) _Pragma("unroll") for (int n = 0; n < 2; ++n) _Pragma("unroll") for (int k = 0; k < 2; ++k) \
;         acc[ai][bj][m][n] = __builtin_amdgcn_mfma_f32_16x16x32_bf16(Bt[n][k], At[m][k], acc[ai][bj][m][n], 0, 0, 0); __builtin_amdgcn_s_setprio(0); } while (0)
; #define PG8_WAIT_V(n) asm volatile("s_waitcnt vmcnt(" #n ")" ::: "memory")
; #define PG8_WAIT_L(n) asm volatile("s_waitcnt lgkmcnt(" #n ")" ::: "memory")
; #define PG8_BAR __builtin_amdgcn_s_barrier()
; #define PG8_SCHED __builtin_amdgcn_sched_barrier(0)
; template <class Epi, class Sched>
; __device__ __forceinline__ void gemm_phase(LAS unsigned char* lds, const Gemm g, const Sched& S, const Epi& E, const int tid) {
;     ...
;             PG8_LDA(At, 1, 1); PG8_STAGE(PG8_SB(1, 0), b3, voffB); PG8_STAGE(PG8_SB(1, 1), b3 + hstepB, voffB); PG8_STAGE(PG8_SA(1, 0), a3, voffA);
;             PG8_WAIT_V(8); PG8_WAIT_L(0); PG8_BAR; PG8_MMA(1, 0, At, B0); PG8_MMA(1, 1, At, B1); PG8_BAR; PG8_SCHED;
;         }
	s_add_i32 s14, s72, s62
	v_lshl_add_u64 v[144:145], v[144:145], 0, s[90:91]
	s_mov_b32 m0, s14
	ds_read_b128 v[186:189], v156 offset:49152
	ds_read_b128 v[190:193], v156 offset:50176
	ds_read_b128 v[204:207], v156 offset:51200
	ds_read_b128 v[208:211], v156 offset:52224
	ds_read_b128 v[212:215], v156 offset:53248
	ds_read_b128 v[216:219], v156 offset:54272
	ds_read_b128 v[220:223], v156 offset:55296
	ds_read_b128 v[230:233], v156 offset:56320
	global_load_lds_dwordx4 v[144:145], off
	s_add_i32 m0, s14, 0x2000
	s_add_u32 s14, s52, 0x80080
	v_lshl_add_u64 v[144:145], v[194:195], 0, s[90:91]
	s_addc_u32 s15, s53, 0
	s_add_i32 s52, s73, s62
	global_load_lds_dwordx4 v[144:145], off
	v_lshl_add_u64 v[144:145], s[14:15], 0, v[0:1]
	s_mov_b32 m0, s52
	s_nop 0
	global_load_lds_dwordx4 v[144:145], off
	v_lshl_add_u64 v[144:145], s[14:15], 0, v[134:135]
	s_add_i32 m0, s52, 0x2000
	s_nop 0
	global_load_lds_dwordx4 v[144:145], off
	v_lshl_add_u64 v[144:145], v[196:197], 0, s[90:91]
	s_mov_b32 m0, s66
	s_nop 0
	global_load_lds_dwordx4 v[144:145], off
	v_lshl_add_u64 v[144:145], v[198:199], 0, s[90:91]
	s_mov_b32 m0, s67
	s_nop 0
	global_load_lds_dwordx4 v[144:145], off
	s_waitcnt vmcnt(8)
	s_waitcnt lgkmcnt(0)
	s_barrier
	s_setprio 1
	s_waitcnt lgkmcnt(0)
	v_mfma_f32_16x16x32_bf16 v[62:65], v[140:143], v[186:189], v[62:65]
	v_mfma_f32_16x16x32_bf16 v[58:61], v[162:165], v[186:189], v[58:61]
	v_mfma_f32_16x16x32_bf16 v[46:49], v[140:143], v[204:207], v[46:49]
	v_mfma_f32_16x16x32_bf16 v[42:45], v[162:165], v[204:207], v[42:45]
	v_mfma_f32_16x16x32_bf16 v[30:33], v[140:143], v[212:215], v[30:33]
	v_mfma_f32_16x16x32_bf16 v[26:29], v[162:165], v[212:215], v[26:29]
	v_mfma_f32_16x16x32_bf16 v[14:17], v[140:143], v[220:223], v[14:17]
	v_mfma_f32_16x16x32_bf16 v[10:13], v[162:165], v[220:223], v[10:13]
	v_mfma_f32_16x16x32_bf16 v[62:65], v[158:161], v[190:193], v[62:65]
	v_mfma_f32_16x16x32_bf16 v[58:61], v[166:169], v[190:193], v[58:61]
	v_mfma_f32_16x16x32_bf16 v[46:49], v[158:161], v[208:211], v[46:49]
	v_mfma_f32_16x16x32_bf16 v[42:45], v[166:169], v[208:211], v[42:45]
	v_mfma_f32_16x16x32_bf16 v[30:33], v[158:161], v[216:219], v[30:33]
	v_mfma_f32_16x16x32_bf16 v[26:29], v[166:169], v[216:219], v[26:29]
	v_mfma_f32_16x16x32_bf16 v[14:17], v[158:161], v[230:233], v[14:17]
	v_mfma_f32_16x16x32_bf16 v[10:13], v[166:169], v[230:233], v[10:13]
	s_setprio 0
	s_setprio 1
	v_mfma_f32_16x16x32_bf16 v[54:57], v[170:173], v[186:189], v[54:57]
	v_mfma_f32_16x16x32_bf16 v[50:53], v[178:181], v[186:189], v[50:53]
	v_mfma_f32_16x16x32_bf16 v[38:41], v[170:173], v[204:207], v[38:41]
	v_mfma_f32_16x16x32_bf16 v[34:37], v[178:181], v[204:207], v[34:37]
	v_mfma_f32_16x16x32_bf16 v[22:25], v[170:173], v[212:215], v[22:25]
	v_mfma_f32_16x16x32_bf16 v[18:21], v[178:181], v[212:215], v[18:21]
	v_mfma_f32_16x16x32_bf16 v[6:9], v[170:173], v[220:223], v[6:9]
	v_mfma_f32_16x16x32_bf16 v[2:5], v[178:181], v[220:223], v[2:5]
	v_mfma_f32_16x16x32_bf16 v[54:57], v[174:177], v[190:193], v[54:57]
	v_mfma_f32_16x16x32_bf16 v[50:53], v[182:185], v[190:193], v[50:53]
	v_mfma_f32_16x16x32_bf16 v[38:41], v[174:177], v[208:211], v[38:41]
	v_mfma_f32_16x16x32_bf16 v[34:37], v[182:185], v[208:211], v[34:37]
	v_mfma_f32_16x16x32_bf16 v[22:25], v[174:177], v[216:219], v[22:25]
	v_mfma_f32_16x16x32_bf16 v[18:21], v[182:185], v[216:219], v[18:21]
	v_mfma_f32_16x16x32_bf16 v[6:9], v[174:177], v[230:233], v[6:9]
	v_mfma_f32_16x16x32_bf16 v[2:5], v[182:185], v[230:233], v[2:5]
	s_setprio 0
	s_barrier
	s_add_i32 s71, s71, 2
	s_add_u32 s69, s69, 0x100
	s_addc_u32 s70, s70, 0
	s_add_u32 s48, s48, 0x100
	s_addc_u32 s49, s49, 0
	s_cmp_gt_u32 s71, 29
	s_cbranch_scc0 .LBB1_724
	s_and_b64 vcc, exec, s[6:7]
	s_cbranch_vccz .LBB1_727
	s_barrier
